# GEMM K-loops: scalar/address instructions between the last MFMA and the closing barrier moved behind the barrier; doubled lgkmcnt(0) at MFMA-section head made single (on top of flip removal)
# speedup vs baseline: 1.0046x; 1.0046x over previous
.LBB0_197:
	ds_read_b128 v[144:147], v151
	ds_read_b128 v[154:157], v151 offset:1024
	ds_read_b128 v[158:161], v151 offset:2048
	ds_read_b128 v[162:165], v151 offset:3072
	s_add_u32 s18, s16, 0xfff80080
	s_addc_u32 s19, s17, -1
	s_cmp_eq_u32 s78, 28
	s_cselect_b32 s21, s5, s19
	s_cselect_b32 s20, s9, s18
	s_cselect_b32 s19, s7, s77
	s_cselect_b32 s18, s15, s76
	v_lshl_add_u64 v[198:199], s[16:17], 0, v[136:137]
	s_add_i32 m0, s24, 0xc000
	ds_read_b128 v[166:169], v152
	ds_read_b128 v[170:173], v152 offset:1024
	ds_read_b128 v[174:177], v152 offset:2048
	ds_read_b128 v[178:181], v152 offset:3072
	ds_read_b128 v[182:185], v152 offset:4096
	ds_read_b128 v[186:189], v152 offset:5120
	ds_read_b128 v[190:193], v152 offset:6144
	ds_read_b128 v[194:197], v152 offset:7168
	global_load_lds_dwordx4 v[198:199], off
	v_lshl_add_u64 v[198:199], s[16:17], 0, v[138:139]
	s_add_i32 m0, s24, 0xe000
	s_nop 0
	global_load_lds_dwordx4 v[198:199], off
	s_waitcnt lgkmcnt(8)
	s_barrier
	s_waitcnt lgkmcnt(0)
	v_mfma_f32_16x16x32_f16 v[124:127], v[144:147], v[166:169], v[124:127]
	v_mfma_f32_16x16x32_f16 v[120:123], v[158:161], v[166:169], v[120:123]
	v_mfma_f32_16x16x32_f16 v[108:111], v[144:147], v[174:177], v[108:111]
	v_mfma_f32_16x16x32_f16 v[104:107], v[158:161], v[174:177], v[104:107]
	v_mfma_f32_16x16x32_f16 v[92:95], v[144:147], v[182:185], v[92:95]
	v_mfma_f32_16x16x32_f16 v[88:91], v[158:161], v[182:185], v[88:91]
	v_mfma_f32_16x16x32_f16 v[76:79], v[144:147], v[190:193], v[76:79]
	v_mfma_f32_16x16x32_f16 v[72:75], v[158:161], v[190:193], v[72:75]
	v_mfma_f32_16x16x32_f16 v[124:127], v[154:157], v[170:173], v[124:127]
	v_mfma_f32_16x16x32_f16 v[120:123], v[162:165], v[170:173], v[120:123]
	v_mfma_f32_16x16x32_f16 v[108:111], v[154:157], v[178:181], v[108:111]
	v_mfma_f32_16x16x32_f16 v[104:107], v[162:165], v[178:181], v[104:107]
	v_mfma_f32_16x16x32_f16 v[92:95], v[154:157], v[186:189], v[92:95]
	v_mfma_f32_16x16x32_f16 v[88:91], v[162:165], v[186:189], v[88:91]
	v_mfma_f32_16x16x32_f16 v[76:79], v[154:157], v[194:197], v[76:79]
	v_mfma_f32_16x16x32_f16 v[72:75], v[162:165], v[194:197], v[72:75]
	s_barrier
	s_add_i32 s79, s68, s23
	v_lshl_add_u64 v[214:215], s[18:19], 0, v[130:131]
	s_mov_b32 m0, s79
	ds_read_b128 v[198:201], v153
	ds_read_b128 v[202:205], v153 offset:1024
	ds_read_b128 v[206:209], v153 offset:2048
	ds_read_b128 v[210:213], v153 offset:3072
	global_load_lds_dwordx4 v[214:215], off
	v_lshl_add_u64 v[216:217], s[18:19], 0, v[134:135]
	s_add_i32 m0, s79, 0x2000
	s_nop 0
	global_load_lds_dwordx4 v[216:217], off
	s_barrier
	s_waitcnt lgkmcnt(0)
	v_mfma_f32_16x16x32_f16 v[116:119], v[198:201], v[166:169], v[116:119]
	v_mfma_f32_16x16x32_f16 v[112:115], v[206:209], v[166:169], v[112:115]
	v_mfma_f32_16x16x32_f16 v[100:103], v[198:201], v[174:177], v[100:103]
	v_mfma_f32_16x16x32_f16 v[96:99], v[206:209], v[174:177], v[96:99]
	v_mfma_f32_16x16x32_f16 v[84:87], v[198:201], v[182:185], v[84:87]
	v_mfma_f32_16x16x32_f16 v[80:83], v[206:209], v[182:185], v[80:83]
	v_mfma_f32_16x16x32_f16 v[68:71], v[198:201], v[190:193], v[68:71]
	v_mfma_f32_16x16x32_f16 v[64:67], v[206:209], v[190:193], v[64:67]
	v_mfma_f32_16x16x32_f16 v[116:119], v[202:205], v[170:173], v[116:119]
	v_mfma_f32_16x16x32_f16 v[112:115], v[210:213], v[170:173], v[112:115]
	v_mfma_f32_16x16x32_f16 v[100:103], v[202:205], v[178:181], v[100:103]
	v_mfma_f32_16x16x32_f16 v[96:99], v[210:213], v[178:181], v[96:99]
	v_mfma_f32_16x16x32_f16 v[84:87], v[202:205], v[186:189], v[84:87]
	v_mfma_f32_16x16x32_f16 v[80:83], v[210:213], v[186:189], v[80:83]
	v_mfma_f32_16x16x32_f16 v[68:71], v[202:205], v[194:197], v[68:71]
	v_mfma_f32_16x16x32_f16 v[64:67], v[210:213], v[194:197], v[64:67]
	s_barrier
	s_mov_b32 m0, s24
	v_lshl_add_u64 v[218:219], s[20:21], 0, v[128:129]
	ds_read_b128 v[166:169], v152 offset:16384
	ds_read_b128 v[170:173], v152 offset:17408
	ds_read_b128 v[174:177], v152 offset:18432
	ds_read_b128 v[178:181], v152 offset:19456
	ds_read_b128 v[182:185], v152 offset:20480
	ds_read_b128 v[186:189], v152 offset:21504
	ds_read_b128 v[190:193], v152 offset:22528
	ds_read_b128 v[194:197], v152 offset:23552
	global_load_lds_dwordx4 v[218:219], off
	v_lshl_add_u64 v[220:221], s[20:21], 0, v[132:133]
	s_mov_b32 m0, s25
	s_nop 0
	global_load_lds_dwordx4 v[220:221], off
	s_barrier
	s_waitcnt lgkmcnt(0)
	v_mfma_f32_16x16x32_f16 v[60:63], v[144:147], v[166:169], v[60:63]
	v_mfma_f32_16x16x32_f16 v[56:59], v[158:161], v[166:169], v[56:59]
	v_mfma_f32_16x16x32_f16 v[44:47], v[144:147], v[174:177], v[44:47]
	v_mfma_f32_16x16x32_f16 v[40:43], v[158:161], v[174:177], v[40:43]
	v_mfma_f32_16x16x32_f16 v[28:31], v[144:147], v[182:185], v[28:31]
	v_mfma_f32_16x16x32_f16 v[24:27], v[158:161], v[182:185], v[24:27]
	v_mfma_f32_16x16x32_f16 v[12:15], v[144:147], v[190:193], v[12:15]
	v_mfma_f32_16x16x32_f16 v[8:11], v[158:161], v[190:193], v[8:11]
	v_mfma_f32_16x16x32_f16 v[60:63], v[154:157], v[170:173], v[60:63]
	v_mfma_f32_16x16x32_f16 v[56:59], v[162:165], v[170:173], v[56:59]
	v_mfma_f32_16x16x32_f16 v[44:47], v[154:157], v[178:181], v[44:47]
	v_mfma_f32_16x16x32_f16 v[40:43], v[162:165], v[178:181], v[40:43]
	v_mfma_f32_16x16x32_f16 v[28:31], v[154:157], v[186:189], v[28:31]
	v_mfma_f32_16x16x32_f16 v[24:27], v[162:165], v[186:189], v[24:27]
	v_mfma_f32_16x16x32_f16 v[12:15], v[154:157], v[194:197], v[12:15]
	v_mfma_f32_16x16x32_f16 v[8:11], v[162:165], v[194:197], v[8:11]
	s_barrier
	s_add_u32 s80, s18, 0x80000
	s_addc_u32 s81, s19, 0
	s_add_i32 s79, s69, s23
	v_lshl_add_u64 v[144:145], s[80:81], 0, v[130:131]
	s_mov_b32 m0, s79
	s_nop 0
	global_load_lds_dwordx4 v[144:145], off
	v_lshl_add_u64 v[144:145], s[80:81], 0, v[134:135]
	s_add_i32 m0, s79, 0x2000
	s_nop 0
	global_load_lds_dwordx4 v[144:145], off
	s_waitcnt vmcnt(6)
	s_barrier
	v_mfma_f32_16x16x32_f16 v[52:55], v[198:201], v[166:169], v[52:55]
	v_mfma_f32_16x16x32_f16 v[48:51], v[206:209], v[166:169], v[48:51]
	v_mfma_f32_16x16x32_f16 v[36:39], v[198:201], v[174:177], v[36:39]
	v_mfma_f32_16x16x32_f16 v[32:35], v[206:209], v[174:177], v[32:35]
	v_mfma_f32_16x16x32_f16 v[20:23], v[198:201], v[182:185], v[20:23]
	v_mfma_f32_16x16x32_f16 v[16:19], v[206:209], v[182:185], v[16:19]
	v_mfma_f32_16x16x32_f16 v[4:7], v[198:201], v[190:193], v[4:7]
	v_mfma_f32_16x16x32_f16 v[0:3], v[206:209], v[190:193], v[0:3]
	v_mfma_f32_16x16x32_f16 v[52:55], v[202:205], v[170:173], v[52:55]
	v_mfma_f32_16x16x32_f16 v[48:51], v[210:213], v[170:173], v[48:51]
	v_mfma_f32_16x16x32_f16 v[36:39], v[202:205], v[178:181], v[36:39]
	v_mfma_f32_16x16x32_f16 v[32:35], v[210:213], v[178:181], v[32:35]
	v_mfma_f32_16x16x32_f16 v[20:23], v[202:205], v[186:189], v[20:23]
	v_mfma_f32_16x16x32_f16 v[16:19], v[210:213], v[186:189], v[16:19]
	v_mfma_f32_16x16x32_f16 v[4:7], v[202:205], v[194:197], v[4:7]
	v_mfma_f32_16x16x32_f16 v[0:3], v[210:213], v[194:197], v[0:3]
	s_barrier
	s_add_i32 s79, 0, 0x18000
	v_add_u32_e32 v162, s79, v149
	ds_read_b128 v[144:147], v162
	ds_read_b128 v[154:157], v162 offset:1024
	ds_read_b128 v[158:161], v162 offset:2048
	ds_read_b128 v[162:165], v162 offset:3072
	s_add_u32 s20, s20, 0x80000
	s_addc_u32 s21, s21, 0
	s_mov_b32 m0, s26
	v_lshl_add_u64 v[198:199], s[20:21], 0, v[128:129]
	ds_read_b128 v[166:169], v152 offset:32768
	ds_read_b128 v[170:173], v152 offset:33792
	ds_read_b128 v[174:177], v152 offset:34816
	ds_read_b128 v[178:181], v152 offset:35840
	ds_read_b128 v[182:185], v152 offset:36864
	ds_read_b128 v[186:189], v152 offset:37888
	ds_read_b128 v[190:193], v152 offset:38912
	ds_read_b128 v[194:197], v152 offset:39936
	global_load_lds_dwordx4 v[198:199], off
	v_lshl_add_u64 v[198:199], s[20:21], 0, v[132:133]
	s_mov_b32 m0, s27
	s_nop 0
	global_load_lds_dwordx4 v[198:199], off
	s_waitcnt lgkmcnt(8)
	s_barrier
	s_waitcnt lgkmcnt(0)
	v_mfma_f32_16x16x32_f16 v[124:127], v[144:147], v[166:169], v[124:127]
	v_mfma_f32_16x16x32_f16 v[120:123], v[158:161], v[166:169], v[120:123]
	v_mfma_f32_16x16x32_f16 v[108:111], v[144:147], v[174:177], v[108:111]
	v_mfma_f32_16x16x32_f16 v[104:107], v[158:161], v[174:177], v[104:107]
	v_mfma_f32_16x16x32_f16 v[92:95], v[144:147], v[182:185], v[92:95]
	v_mfma_f32_16x16x32_f16 v[88:91], v[158:161], v[182:185], v[88:91]
	v_mfma_f32_16x16x32_f16 v[76:79], v[144:147], v[190:193], v[76:79]
	v_mfma_f32_16x16x32_f16 v[72:75], v[158:161], v[190:193], v[72:75]
	v_mfma_f32_16x16x32_f16 v[124:127], v[154:157], v[170:173], v[124:127]
	v_mfma_f32_16x16x32_f16 v[120:123], v[162:165], v[170:173], v[120:123]
	v_mfma_f32_16x16x32_f16 v[108:111], v[154:157], v[178:181], v[108:111]
	v_mfma_f32_16x16x32_f16 v[104:107], v[162:165], v[178:181], v[104:107]
	v_mfma_f32_16x16x32_f16 v[92:95], v[154:157], v[186:189], v[92:95]
	v_mfma_f32_16x16x32_f16 v[88:91], v[162:165], v[186:189], v[88:91]
	v_mfma_f32_16x16x32_f16 v[76:79], v[154:157], v[194:197], v[76:79]
	v_mfma_f32_16x16x32_f16 v[72:75], v[162:165], v[194:197], v[72:75]
	s_barrier
	s_add_i32 s20, 0, 0x1c000
	s_add_i32 s21, s79, s23
	v_add_u32_e32 v210, s20, v149
	v_lshl_add_u64 v[214:215], v[214:215], 0, s[0:1]
	s_mov_b32 m0, s21
	ds_read_b128 v[198:201], v210
	ds_read_b128 v[202:205], v210 offset:1024
	ds_read_b128 v[206:209], v210 offset:2048
	ds_read_b128 v[210:213], v210 offset:3072
	global_load_lds_dwordx4 v[214:215], off
	v_lshl_add_u64 v[214:215], v[216:217], 0, s[0:1]
	s_add_i32 m0, s21, 0x2000
	s_nop 0
	global_load_lds_dwordx4 v[214:215], off
	s_barrier
	s_waitcnt lgkmcnt(0)
	v_mfma_f32_16x16x32_f16 v[116:119], v[198:201], v[166:169], v[116:119]
	v_mfma_f32_16x16x32_f16 v[112:115], v[206:209], v[166:169], v[112:115]
	v_mfma_f32_16x16x32_f16 v[100:103], v[198:201], v[174:177], v[100:103]
	v_mfma_f32_16x16x32_f16 v[96:99], v[206:209], v[174:177], v[96:99]
	v_mfma_f32_16x16x32_f16 v[84:87], v[198:201], v[182:185], v[84:87]
	v_mfma_f32_16x16x32_f16 v[80:83], v[206:209], v[182:185], v[80:83]
	v_mfma_f32_16x16x32_f16 v[68:71], v[198:201], v[190:193], v[68:71]
	v_mfma_f32_16x16x32_f16 v[64:67], v[206:209], v[190:193], v[64:67]
	v_mfma_f32_16x16x32_f16 v[116:119], v[202:205], v[170:173], v[116:119]
	v_mfma_f32_16x16x32_f16 v[112:115], v[210:213], v[170:173], v[112:115]
	v_mfma_f32_16x16x32_f16 v[100:103], v[202:205], v[178:181], v[100:103]
	v_mfma_f32_16x16x32_f16 v[96:99], v[210:213], v[178:181], v[96:99]
	v_mfma_f32_16x16x32_f16 v[84:87], v[202:205], v[186:189], v[84:87]
	v_mfma_f32_16x16x32_f16 v[80:83], v[210:213], v[186:189], v[80:83]
	v_mfma_f32_16x16x32_f16 v[68:71], v[202:205], v[194:197], v[68:71]
	v_mfma_f32_16x16x32_f16 v[64:67], v[210:213], v[194:197], v[64:67]
	s_barrier
	s_mov_b32 m0, s29
	v_lshl_add_u64 v[214:215], v[218:219], 0, s[0:1]
	ds_read_b128 v[166:169], v152 offset:49152
	ds_read_b128 v[170:173], v152 offset:50176
	ds_read_b128 v[174:177], v152 offset:51200
	ds_read_b128 v[178:181], v152 offset:52224
	ds_read_b128 v[182:185], v152 offset:53248
	ds_read_b128 v[186:189], v152 offset:54272
	ds_read_b128 v[190:193], v152 offset:55296
	ds_read_b128 v[194:197], v152 offset:56320
	global_load_lds_dwordx4 v[214:215], off
	v_lshl_add_u64 v[214:215], v[220:221], 0, s[0:1]
	s_mov_b32 m0, s30
	s_nop 0
	global_load_lds_dwordx4 v[214:215], off
	s_barrier
	s_waitcnt lgkmcnt(0)
	v_mfma_f32_16x16x32_f16 v[60:63], v[144:147], v[166:169], v[60:63]
	v_mfma_f32_16x16x32_f16 v[56:59], v[158:161], v[166:169], v[56:59]
	v_mfma_f32_16x16x32_f16 v[44:47], v[144:147], v[174:177], v[44:47]
	v_mfma_f32_16x16x32_f16 v[40:43], v[158:161], v[174:177], v[40:43]
	v_mfma_f32_16x16x32_f16 v[28:31], v[144:147], v[182:185], v[28:31]
	v_mfma_f32_16x16x32_f16 v[24:27], v[158:161], v[182:185], v[24:27]
	v_mfma_f32_16x16x32_f16 v[12:15], v[144:147], v[190:193], v[12:15]
	v_mfma_f32_16x16x32_f16 v[8:11], v[158:161], v[190:193], v[8:11]
	v_mfma_f32_16x16x32_f16 v[60:63], v[154:157], v[170:173], v[60:63]
	v_mfma_f32_16x16x32_f16 v[56:59], v[162:165], v[170:173], v[56:59]
	v_mfma_f32_16x16x32_f16 v[44:47], v[154:157], v[178:181], v[44:47]
	v_mfma_f32_16x16x32_f16 v[40:43], v[162:165], v[178:181], v[40:43]
	v_mfma_f32_16x16x32_f16 v[28:31], v[154:157], v[186:189], v[28:31]
	v_mfma_f32_16x16x32_f16 v[24:27], v[162:165], v[186:189], v[24:27]
	v_mfma_f32_16x16x32_f16 v[12:15], v[154:157], v[194:197], v[12:15]
	v_mfma_f32_16x16x32_f16 v[8:11], v[162:165], v[194:197], v[8:11]
	s_barrier
	s_add_u32 s18, s18, 0x80080
	s_addc_u32 s19, s19, 0
	s_add_i32 s20, s20, s23
	v_lshl_add_u64 v[144:145], s[18:19], 0, v[130:131]
	s_mov_b32 m0, s20
	s_nop 0
	global_load_lds_dwordx4 v[144:145], off
	v_lshl_add_u64 v[144:145], s[18:19], 0, v[134:135]
	s_add_i32 m0, s20, 0x2000
	s_nop 0
	global_load_lds_dwordx4 v[144:145], off
	s_waitcnt vmcnt(6)
	s_barrier
	v_mfma_f32_16x16x32_f16 v[52:55], v[198:201], v[166:169], v[52:55]
	v_mfma_f32_16x16x32_f16 v[48:51], v[206:209], v[166:169], v[48:51]
	v_mfma_f32_16x16x32_f16 v[36:39], v[198:201], v[174:177], v[36:39]
	v_mfma_f32_16x16x32_f16 v[32:35], v[206:209], v[174:177], v[32:35]
	v_mfma_f32_16x16x32_f16 v[20:23], v[198:201], v[182:185], v[20:23]
	v_mfma_f32_16x16x32_f16 v[16:19], v[206:209], v[182:185], v[16:19]
	v_mfma_f32_16x16x32_f16 v[4:7], v[198:201], v[190:193], v[4:7]
	v_mfma_f32_16x16x32_f16 v[0:3], v[206:209], v[190:193], v[0:3]
	v_mfma_f32_16x16x32_f16 v[52:55], v[202:205], v[170:173], v[52:55]
	v_mfma_f32_16x16x32_f16 v[48:51], v[210:213], v[170:173], v[48:51]
	v_mfma_f32_16x16x32_f16 v[36:39], v[202:205], v[178:181], v[36:39]
	v_mfma_f32_16x16x32_f16 v[32:35], v[210:213], v[178:181], v[32:35]
	v_mfma_f32_16x16x32_f16 v[20:23], v[202:205], v[186:189], v[20:23]
	v_mfma_f32_16x16x32_f16 v[16:19], v[210:213], v[186:189], v[16:19]
	v_mfma_f32_16x16x32_f16 v[4:7], v[202:205], v[194:197], v[4:7]
	v_mfma_f32_16x16x32_f16 v[0:3], v[210:213], v[194:197], v[0:3]
	s_barrier
	s_add_i32 s78, s78, 2
	s_add_u32 s16, s16, 0x100
	s_addc_u32 s17, s17, 0
	s_add_u32 s76, s76, 0x100
	s_addc_u32 s77, s77, 0
	s_cmp_gt_u32 s78, 29
	s_cbranch_scc0 .LBB0_197
	s_setprio 0
	v_readlane_b32 s52, v254, 21
	v_readlane_b32 s54, v254, 23
	v_readlane_b32 s55, v254, 24
	v_lshl_add_u32 v154, s14, 8, v148
	v_lshl_or_b32 v144, s4, 8, v150
	v_mov_b64_e32 v[146:147], s[54:55]
	v_mad_i64_i32 v[146:147], s[4:5], v154, s70, v[146:147]
	v_cmp_gt_i32_e32 vcc, s71, v144
	v_ashrrev_i32_e32 v145, 31, v144
	v_readlane_b32 s53, v254, 22
	v_readlane_b32 s56, v254, 25
	v_readlane_b32 s57, v254, 26
	v_readlane_b32 s58, v254, 27
	v_readlane_b32 s59, v254, 28
	v_readlane_b32 s60, v254, 29
	v_readlane_b32 s61, v254, 30
	v_readlane_b32 s62, v254, 31
	v_readlane_b32 s63, v254, 32
	v_readlane_b32 s64, v254, 33
	v_readlane_b32 s65, v254, 34
	v_readlane_b32 s66, v254, 35
	v_readlane_b32 s67, v254, 36
	s_and_saveexec_b64 s[4:5], vcc
	s_cbranch_execz .LBB0_200
	v_cvt_pk_f16_f32 v123, v122, v123
	v_cvt_pk_f16_f32 v122, v120, v121
	v_cvt_pk_f16_f32 v121, v126, v127
	v_cvt_pk_f16_f32 v120, v124, v125
	v_lshl_add_u64 v[124:125], v[144:145], 1, v[146:147]
	global_store_dwordx4 v[124:125], v[120:123], off

.LBB0_647:
	ds_read_b128 v[80:83], v243
	ds_read_b128 v[88:91], v243 offset:1024
	ds_read_b128 v[96:99], v243 offset:2048
	ds_read_b128 v[100:103], v243 offset:3072
	s_add_u32 s18, s16, 0xfff80080
	s_addc_u32 s19, s17, -1
	s_cmp_eq_u32 s80, 28
	s_cselect_b32 s21, s9, s19
	s_cselect_b32 s20, s31, s18
	s_cselect_b32 s19, s7, s79
	s_cselect_b32 s18, s77, s78
	v_lshl_add_u64 v[176:177], s[16:17], 0, v[212:213]
	s_add_i32 m0, s15, 0xc000
	ds_read_b128 v[120:123], v244
	ds_read_b128 v[132:135], v244 offset:1024
	ds_read_b128 v[136:139], v244 offset:2048
	ds_read_b128 v[148:151], v244 offset:3072
	ds_read_b128 v[152:155], v244 offset:4096
	ds_read_b128 v[156:159], v244 offset:5120
	ds_read_b128 v[160:163], v244 offset:6144
	ds_read_b128 v[172:175], v244 offset:7168
	global_load_lds_dwordx4 v[176:177], off
	v_lshl_add_u64 v[176:177], s[16:17], 0, v[214:215]
	s_add_i32 m0, s15, 0xe000
	s_nop 0
	global_load_lds_dwordx4 v[176:177], off
	s_waitcnt lgkmcnt(8)
	s_barrier
	s_waitcnt lgkmcnt(0)
	v_mfma_f32_16x16x32_f16 v[168:171], v[80:83], v[120:123], v[168:171]
	v_mfma_f32_16x16x32_f16 v[164:167], v[96:99], v[120:123], v[164:167]
	v_mfma_f32_16x16x32_f16 v[128:131], v[80:83], v[136:139], v[128:131]
	v_mfma_f32_16x16x32_f16 v[124:127], v[96:99], v[136:139], v[124:127]
	v_mfma_f32_16x16x32_f16 v[108:111], v[80:83], v[152:155], v[108:111]
	v_mfma_f32_16x16x32_f16 v[104:107], v[96:99], v[152:155], v[104:107]
	v_mfma_f32_16x16x32_f16 v[76:79], v[80:83], v[160:163], v[76:79]
	v_mfma_f32_16x16x32_f16 v[72:75], v[96:99], v[160:163], v[72:75]
	v_mfma_f32_16x16x32_f16 v[168:171], v[88:91], v[132:135], v[168:171]
	v_mfma_f32_16x16x32_f16 v[164:167], v[100:103], v[132:135], v[164:167]
	v_mfma_f32_16x16x32_f16 v[128:131], v[88:91], v[148:151], v[128:131]
	v_mfma_f32_16x16x32_f16 v[124:127], v[100:103], v[148:151], v[124:127]
	v_mfma_f32_16x16x32_f16 v[108:111], v[88:91], v[156:159], v[108:111]
	v_mfma_f32_16x16x32_f16 v[104:107], v[100:103], v[156:159], v[104:107]
	v_mfma_f32_16x16x32_f16 v[76:79], v[88:91], v[172:175], v[76:79]
	v_mfma_f32_16x16x32_f16 v[72:75], v[100:103], v[172:175], v[72:75]
	s_barrier
	s_add_i32 s81, s71, s24
	v_lshl_add_u64 v[196:197], s[18:19], 0, v[206:207]
	s_mov_b32 m0, s81
	ds_read_b128 v[176:179], v245
	ds_read_b128 v[180:183], v245 offset:1024
	ds_read_b128 v[184:187], v245 offset:2048
	ds_read_b128 v[188:191], v245 offset:3072
	global_load_lds_dwordx4 v[196:197], off
	v_lshl_add_u64 v[198:199], s[18:19], 0, v[210:211]
	s_add_i32 m0, s81, 0x2000
	s_nop 0
	global_load_lds_dwordx4 v[198:199], off
	s_barrier
	s_waitcnt lgkmcnt(0)
	v_mfma_f32_16x16x32_f16 v[144:147], v[176:179], v[120:123], v[144:147]
	v_mfma_f32_16x16x32_f16 v[116:119], v[176:179], v[136:139], v[116:119]
	v_mfma_f32_16x16x32_f16 v[112:115], v[184:187], v[136:139], v[112:115]
	v_mfma_f32_16x16x32_f16 v[92:95], v[176:179], v[152:155], v[92:95]
	v_mfma_f32_16x16x32_f16 v[84:87], v[184:187], v[152:155], v[84:87]
	v_mfma_f32_16x16x32_f16 v[68:71], v[176:179], v[160:163], v[68:71]
	v_mfma_f32_16x16x32_f16 v[64:67], v[184:187], v[160:163], v[64:67]
	v_mfma_f32_16x16x32_f16 v[144:147], v[180:183], v[132:135], v[144:147]
	v_mfma_f32_16x16x32_f16 v[120:123], v[184:187], v[120:123], v[140:143]
	v_mfma_f32_16x16x32_f16 v[116:119], v[180:183], v[148:151], v[116:119]
	v_mfma_f32_16x16x32_f16 v[112:115], v[188:191], v[148:151], v[112:115]
	v_mfma_f32_16x16x32_f16 v[92:95], v[180:183], v[156:159], v[92:95]
	v_mfma_f32_16x16x32_f16 v[84:87], v[188:191], v[156:159], v[84:87]
	v_mfma_f32_16x16x32_f16 v[68:71], v[180:183], v[172:175], v[68:71]
	v_mfma_f32_16x16x32_f16 v[64:67], v[188:191], v[172:175], v[64:67]
	v_mfma_f32_16x16x32_f16 v[120:123], v[188:191], v[132:135], v[120:123]
	s_barrier
	s_mov_b32 m0, s15
	v_lshl_add_u64 v[200:201], s[20:21], 0, v[204:205]
	ds_read_b128 v[132:135], v244 offset:16384
	ds_read_b128 v[136:139], v244 offset:17408
	ds_read_b128 v[140:143], v244 offset:18432
	ds_read_b128 v[148:151], v244 offset:19456
	ds_read_b128 v[152:155], v244 offset:20480
	ds_read_b128 v[156:159], v244 offset:21504
	ds_read_b128 v[160:163], v244 offset:22528
	ds_read_b128 v[172:175], v244 offset:23552
	global_load_lds_dwordx4 v[200:201], off
	v_lshl_add_u64 v[202:203], s[20:21], 0, v[208:209]
	s_mov_b32 m0, s25
	s_nop 0
	global_load_lds_dwordx4 v[202:203], off
	s_barrier
	s_waitcnt lgkmcnt(0)
	v_mfma_f32_16x16x32_f16 v[60:63], v[80:83], v[132:135], v[60:63]
	v_mfma_f32_16x16x32_f16 v[56:59], v[96:99], v[132:135], v[56:59]
	v_mfma_f32_16x16x32_f16 v[44:47], v[80:83], v[140:143], v[44:47]
	v_mfma_f32_16x16x32_f16 v[40:43], v[96:99], v[140:143], v[40:43]
	v_mfma_f32_16x16x32_f16 v[28:31], v[80:83], v[152:155], v[28:31]
	v_mfma_f32_16x16x32_f16 v[24:27], v[96:99], v[152:155], v[24:27]
	v_mfma_f32_16x16x32_f16 v[12:15], v[80:83], v[160:163], v[12:15]
	v_mfma_f32_16x16x32_f16 v[8:11], v[96:99], v[160:163], v[8:11]
	v_mfma_f32_16x16x32_f16 v[60:63], v[88:91], v[136:139], v[60:63]
	v_mfma_f32_16x16x32_f16 v[56:59], v[100:103], v[136:139], v[56:59]
	v_mfma_f32_16x16x32_f16 v[44:47], v[88:91], v[148:151], v[44:47]
	v_mfma_f32_16x16x32_f16 v[40:43], v[100:103], v[148:151], v[40:43]
	v_mfma_f32_16x16x32_f16 v[28:31], v[88:91], v[156:159], v[28:31]
	v_mfma_f32_16x16x32_f16 v[24:27], v[100:103], v[156:159], v[24:27]
	v_mfma_f32_16x16x32_f16 v[12:15], v[88:91], v[172:175], v[12:15]
	v_mfma_f32_16x16x32_f16 v[8:11], v[100:103], v[172:175], v[8:11]
	s_barrier
	s_add_u32 s82, s18, 0x80000
	s_addc_u32 s83, s19, 0
	s_add_i32 s81, s76, s24
	v_lshl_add_u64 v[80:81], s[82:83], 0, v[206:207]
	s_mov_b32 m0, s81
	s_nop 0
	global_load_lds_dwordx4 v[80:81], off
	v_lshl_add_u64 v[80:81], s[82:83], 0, v[210:211]
	s_add_i32 m0, s81, 0x2000
	s_nop 0
	global_load_lds_dwordx4 v[80:81], off
	s_waitcnt vmcnt(6)
	s_barrier
	v_mfma_f32_16x16x32_f16 v[52:55], v[176:179], v[132:135], v[52:55]
	v_mfma_f32_16x16x32_f16 v[48:51], v[184:187], v[132:135], v[48:51]
	v_mfma_f32_16x16x32_f16 v[36:39], v[176:179], v[140:143], v[36:39]
	v_mfma_f32_16x16x32_f16 v[32:35], v[184:187], v[140:143], v[32:35]
	v_mfma_f32_16x16x32_f16 v[20:23], v[176:179], v[152:155], v[20:23]
	v_mfma_f32_16x16x32_f16 v[16:19], v[184:187], v[152:155], v[16:19]
	v_mfma_f32_16x16x32_f16 v[4:7], v[176:179], v[160:163], v[4:7]
	v_mfma_f32_16x16x32_f16 v[0:3], v[184:187], v[160:163], v[0:3]
	v_mfma_f32_16x16x32_f16 v[52:55], v[180:183], v[136:139], v[52:55]
	v_mfma_f32_16x16x32_f16 v[48:51], v[188:191], v[136:139], v[48:51]
	v_mfma_f32_16x16x32_f16 v[36:39], v[180:183], v[148:151], v[36:39]
	v_mfma_f32_16x16x32_f16 v[32:35], v[188:191], v[148:151], v[32:35]
	v_mfma_f32_16x16x32_f16 v[20:23], v[180:183], v[156:159], v[20:23]
	v_mfma_f32_16x16x32_f16 v[16:19], v[188:191], v[156:159], v[16:19]
	v_mfma_f32_16x16x32_f16 v[4:7], v[180:183], v[172:175], v[4:7]
	v_mfma_f32_16x16x32_f16 v[0:3], v[188:191], v[172:175], v[0:3]
	s_barrier
	s_add_i32 s81, 0, 0x18000
	v_add_u32_e32 v100, s81, v241
	ds_read_b128 v[80:83], v100
	ds_read_b128 v[88:91], v100 offset:1024
	ds_read_b128 v[96:99], v100 offset:2048
	ds_read_b128 v[100:103], v100 offset:3072
	s_add_u32 s20, s20, 0x80000
	s_addc_u32 s21, s21, 0
	s_mov_b32 m0, s26
	v_lshl_add_u64 v[140:141], s[20:21], 0, v[204:205]
	ds_read_b128 v[132:135], v244 offset:32768
	ds_read_b128 v[136:139], v244 offset:33792
	ds_read_b128 v[148:151], v244 offset:34816
	ds_read_b128 v[152:155], v244 offset:35840
	ds_read_b128 v[156:159], v244 offset:36864
	ds_read_b128 v[160:163], v244 offset:37888
	ds_read_b128 v[172:175], v244 offset:38912
	ds_read_b128 v[176:179], v244 offset:39936
	global_load_lds_dwordx4 v[140:141], off
	v_lshl_add_u64 v[140:141], s[20:21], 0, v[208:209]
	s_mov_b32 m0, s27
	s_nop 0
	global_load_lds_dwordx4 v[140:141], off
	s_waitcnt lgkmcnt(8)
	s_barrier
	s_waitcnt lgkmcnt(0)
	v_mfma_f32_16x16x32_f16 v[140:143], v[80:83], v[132:135], v[168:171]
	v_mfma_f32_16x16x32_f16 v[168:171], v[88:91], v[136:139], v[140:143]
	v_mfma_f32_16x16x32_f16 v[140:143], v[96:99], v[132:135], v[164:167]
	v_mfma_f32_16x16x32_f16 v[128:131], v[80:83], v[148:151], v[128:131]
	v_mfma_f32_16x16x32_f16 v[124:127], v[96:99], v[148:151], v[124:127]
	v_mfma_f32_16x16x32_f16 v[108:111], v[80:83], v[156:159], v[108:111]
	v_mfma_f32_16x16x32_f16 v[104:107], v[96:99], v[156:159], v[104:107]
	v_mfma_f32_16x16x32_f16 v[76:79], v[80:83], v[172:175], v[76:79]
	v_mfma_f32_16x16x32_f16 v[72:75], v[96:99], v[172:175], v[72:75]
	v_mfma_f32_16x16x32_f16 v[164:167], v[100:103], v[136:139], v[140:143]
	v_mfma_f32_16x16x32_f16 v[128:131], v[88:91], v[152:155], v[128:131]
	v_mfma_f32_16x16x32_f16 v[124:127], v[100:103], v[152:155], v[124:127]
	v_mfma_f32_16x16x32_f16 v[108:111], v[88:91], v[160:163], v[108:111]
	v_mfma_f32_16x16x32_f16 v[104:107], v[100:103], v[160:163], v[104:107]
	v_mfma_f32_16x16x32_f16 v[76:79], v[88:91], v[176:179], v[76:79]
	v_mfma_f32_16x16x32_f16 v[72:75], v[100:103], v[176:179], v[72:75]
	s_barrier
	s_add_i32 s20, 0, 0x1c000
	v_add_u32_e32 v140, s20, v241
	s_add_i32 s21, s81, s24
	ds_read_b128 v[180:183], v140
	ds_read_b128 v[184:187], v140 offset:1024
	ds_read_b128 v[188:191], v140 offset:2048
	ds_read_b128 v[192:195], v140 offset:3072
	v_lshl_add_u64 v[140:141], v[196:197], 0, s[4:5]
	s_mov_b32 m0, s21
	s_nop 0
	global_load_lds_dwordx4 v[140:141], off
	v_lshl_add_u64 v[140:141], v[198:199], 0, s[4:5]
	s_add_i32 m0, s21, 0x2000
	s_nop 0
	global_load_lds_dwordx4 v[140:141], off
	s_barrier
	s_waitcnt lgkmcnt(0)
	v_mfma_f32_16x16x32_f16 v[140:143], v[180:183], v[132:135], v[144:147]
	v_mfma_f32_16x16x32_f16 v[120:123], v[188:191], v[132:135], v[120:123]
	v_mfma_f32_16x16x32_f16 v[116:119], v[180:183], v[148:151], v[116:119]
	v_mfma_f32_16x16x32_f16 v[112:115], v[188:191], v[148:151], v[112:115]
	v_mfma_f32_16x16x32_f16 v[92:95], v[180:183], v[156:159], v[92:95]
	v_mfma_f32_16x16x32_f16 v[84:87], v[188:191], v[156:159], v[84:87]
	v_mfma_f32_16x16x32_f16 v[68:71], v[180:183], v[172:175], v[68:71]
	v_mfma_f32_16x16x32_f16 v[64:67], v[188:191], v[172:175], v[64:67]
	v_mfma_f32_16x16x32_f16 v[144:147], v[184:187], v[136:139], v[140:143]
	v_mfma_f32_16x16x32_f16 v[140:143], v[192:195], v[136:139], v[120:123]
	v_mfma_f32_16x16x32_f16 v[116:119], v[184:187], v[152:155], v[116:119]
	v_mfma_f32_16x16x32_f16 v[112:115], v[192:195], v[152:155], v[112:115]
	v_mfma_f32_16x16x32_f16 v[92:95], v[184:187], v[160:163], v[92:95]
	v_mfma_f32_16x16x32_f16 v[84:87], v[192:195], v[160:163], v[84:87]
	v_mfma_f32_16x16x32_f16 v[68:71], v[184:187], v[176:179], v[68:71]
	v_mfma_f32_16x16x32_f16 v[64:67], v[192:195], v[176:179], v[64:67]
	s_barrier
	s_mov_b32 m0, s35
	v_lshl_add_u64 v[176:177], v[200:201], 0, s[4:5]
	ds_read_b128 v[120:123], v244 offset:49152
	ds_read_b128 v[132:135], v244 offset:50176
	ds_read_b128 v[136:139], v244 offset:51200
	ds_read_b128 v[148:151], v244 offset:52224
	ds_read_b128 v[152:155], v244 offset:53248
	ds_read_b128 v[156:159], v244 offset:54272
	ds_read_b128 v[160:163], v244 offset:55296
	ds_read_b128 v[172:175], v244 offset:56320
	global_load_lds_dwordx4 v[176:177], off
	v_lshl_add_u64 v[176:177], v[202:203], 0, s[4:5]
	s_mov_b32 m0, s68
	s_nop 0
	global_load_lds_dwordx4 v[176:177], off
	s_barrier
	s_waitcnt lgkmcnt(0)
	v_mfma_f32_16x16x32_f16 v[60:63], v[80:83], v[120:123], v[60:63]
	v_mfma_f32_16x16x32_f16 v[56:59], v[96:99], v[120:123], v[56:59]
	v_mfma_f32_16x16x32_f16 v[44:47], v[80:83], v[136:139], v[44:47]
	v_mfma_f32_16x16x32_f16 v[40:43], v[96:99], v[136:139], v[40:43]
	v_mfma_f32_16x16x32_f16 v[28:31], v[80:83], v[152:155], v[28:31]
	v_mfma_f32_16x16x32_f16 v[24:27], v[96:99], v[152:155], v[24:27]
	v_mfma_f32_16x16x32_f16 v[12:15], v[80:83], v[160:163], v[12:15]
	v_mfma_f32_16x16x32_f16 v[8:11], v[96:99], v[160:163], v[8:11]
	v_mfma_f32_16x16x32_f16 v[60:63], v[88:91], v[132:135], v[60:63]
	v_mfma_f32_16x16x32_f16 v[56:59], v[100:103], v[132:135], v[56:59]
	v_mfma_f32_16x16x32_f16 v[44:47], v[88:91], v[148:151], v[44:47]
	v_mfma_f32_16x16x32_f16 v[40:43], v[100:103], v[148:151], v[40:43]
	v_mfma_f32_16x16x32_f16 v[28:31], v[88:91], v[156:159], v[28:31]
	v_mfma_f32_16x16x32_f16 v[24:27], v[100:103], v[156:159], v[24:27]
	v_mfma_f32_16x16x32_f16 v[12:15], v[88:91], v[172:175], v[12:15]
	v_mfma_f32_16x16x32_f16 v[8:11], v[100:103], v[172:175], v[8:11]
	s_barrier
	s_add_u32 s18, s18, 0x80080
	s_addc_u32 s19, s19, 0
	s_add_i32 s20, s20, s24
	v_lshl_add_u64 v[80:81], s[18:19], 0, v[206:207]
	s_mov_b32 m0, s20
	s_nop 0
	global_load_lds_dwordx4 v[80:81], off
	v_lshl_add_u64 v[80:81], s[18:19], 0, v[210:211]
	s_add_i32 m0, s20, 0x2000
	s_nop 0
	global_load_lds_dwordx4 v[80:81], off
	s_waitcnt vmcnt(6)
	s_barrier
	v_mfma_f32_16x16x32_f16 v[52:55], v[180:183], v[120:123], v[52:55]
	v_mfma_f32_16x16x32_f16 v[48:51], v[188:191], v[120:123], v[48:51]
	v_mfma_f32_16x16x32_f16 v[36:39], v[180:183], v[136:139], v[36:39]
	v_mfma_f32_16x16x32_f16 v[32:35], v[188:191], v[136:139], v[32:35]
	v_mfma_f32_16x16x32_f16 v[20:23], v[180:183], v[152:155], v[20:23]
	v_mfma_f32_16x16x32_f16 v[16:19], v[188:191], v[152:155], v[16:19]
	v_mfma_f32_16x16x32_f16 v[4:7], v[180:183], v[160:163], v[4:7]
	v_mfma_f32_16x16x32_f16 v[0:3], v[188:191], v[160:163], v[0:3]
	v_mfma_f32_16x16x32_f16 v[52:55], v[184:187], v[132:135], v[52:55]
	v_mfma_f32_16x16x32_f16 v[48:51], v[192:195], v[132:135], v[48:51]
	v_mfma_f32_16x16x32_f16 v[36:39], v[184:187], v[148:151], v[36:39]
	v_mfma_f32_16x16x32_f16 v[32:35], v[192:195], v[148:151], v[32:35]
	v_mfma_f32_16x16x32_f16 v[20:23], v[184:187], v[156:159], v[20:23]
	v_mfma_f32_16x16x32_f16 v[16:19], v[192:195], v[156:159], v[16:19]
	v_mfma_f32_16x16x32_f16 v[4:7], v[184:187], v[172:175], v[4:7]
	v_mfma_f32_16x16x32_f16 v[0:3], v[192:195], v[172:175], v[0:3]
	s_barrier
	s_add_i32 s80, s80, 2
	s_add_u32 s16, s16, 0x100
	s_addc_u32 s17, s17, 0
	s_add_u32 s78, s78, 0x100
	s_addc_u32 s79, s79, 0
	s_cmp_gt_u32 s80, 29
	s_cbranch_scc0 .LBB0_647
	s_setprio 0
	s_lshl_b32 s7, s14, 8
	s_add_i32 s9, s7, 0xffffe000
	s_lshr_b32 s9, s9, 11
	s_mulk_i32 s9, 0x1800
	s_addk_i32 s9, 0x1800
	s_cmp_gt_i32 s14, 31
	s_cselect_b32 s16, s9, 0
	s_ashr_i32 s17, s16, 31
	v_lshl_or_b32 v120, s30, 8, v242
	s_lshl_b64 s[16:17], s[16:17], 2
	s_add_u32 s16, s29, s16
	v_ashrrev_i32_e32 v121, 31, v120
	v_add_u32_e32 v122, s7, v240
	s_addc_u32 s17, s34, s17
	v_lshlrev_b64 v[220:221], 1, v[120:121]
	v_ashrrev_i32_e32 v123, 31, v122
	v_lshl_add_u64 v[88:89], v[120:121], 2, s[16:17]
	v_lshl_add_u64 v[120:121], s[40:41], 0, v[220:221]
	v_lshlrev_b64 v[236:237], 12, v[122:123]
	v_lshl_add_u64 v[132:133], v[120:121], 0, v[236:237]
	global_load_dwordx4 v[96:99], v[88:89], off offset:16
	global_load_dwordx4 v[100:103], v[88:89], off
	global_load_dwordx4 v[80:83], v[88:89], off offset:528
	s_nop 0
	global_load_dwordx4 v[88:91], v[88:89], off offset:512
	s_nop 0
	global_load_dwordx4 v[246:249], v[132:133], off nt
	global_load_dwordx4 v[200:203], v[132:133], off offset:256 nt
	v_or_b32_e32 v132, 16, v122
	v_ashrrev_i32_e32 v133, 31, v132
	v_lshlrev_b64 v[234:235], 12, v[132:133]
	v_lshl_add_u64 v[132:133], v[120:121], 0, v[234:235]
	global_load_dwordx4 v[196:199], v[132:133], off nt
	global_load_dwordx4 v[192:195], v[132:133], off offset:256 nt
	v_or_b32_e32 v132, 32, v122
	v_ashrrev_i32_e32 v133, 31, v132
	v_lshlrev_b64 v[232:233], 12, v[132:133]
	v_lshl_add_u64 v[132:133], v[120:121], 0, v[232:233]
	global_load_dwordx4 v[188:191], v[132:133], off nt
	global_load_dwordx4 v[184:187], v[132:133], off offset:256 nt
	v_or_b32_e32 v122, 48, v122
	v_ashrrev_i32_e32 v123, 31, v122
	v_lshlrev_b64 v[230:231], 12, v[122:123]
	v_lshl_add_u64 v[122:123], v[120:121], 0, v[230:231]
	global_load_dwordx4 v[180:183], v[122:123], off nt
	global_load_dwordx4 v[176:179], v[122:123], off offset:256 nt
	s_mov_b64 s[16:17], 0x80000
	v_lshl_add_u64 v[228:229], v[236:237], 0, s[16:17]
	v_lshl_add_u64 v[122:123], v[120:121], 0, v[228:229]
	global_load_dwordx4 v[172:175], v[122:123], off nt
	global_load_dwordx4 v[160:163], v[122:123], off offset:256 nt
	s_mov_b64 s[16:17], 0x90000
	v_lshl_add_u64 v[226:227], v[236:237], 0, s[16:17]
	v_lshl_add_u64 v[122:123], v[120:121], 0, v[226:227]
	global_load_dwordx4 v[156:159], v[122:123], off nt
	global_load_dwordx4 v[152:155], v[122:123], off offset:256 nt
	s_mov_b64 s[16:17], 0xa0000
	v_lshl_add_u64 v[224:225], v[236:237], 0, s[16:17]
	v_lshl_add_u64 v[122:123], v[120:121], 0, v[224:225]
	global_load_dwordx4 v[148:151], v[122:123], off nt
	global_load_dwordx4 v[136:139], v[122:123], off offset:256 nt
	s_mov_b64 s[16:17], 0xb0000
	v_lshl_add_u64 v[222:223], v[236:237], 0, s[16:17]
	v_lshl_add_u64 v[120:121], v[120:121], 0, v[222:223]
	global_load_dwordx4 v[132:135], v[120:121], off nt
	s_nop 0
	global_load_dwordx4 v[120:123], v[120:121], off offset:256 nt
	s_and_b64 vcc, exec, s[2:3]
	s_mov_b32 s30, s6
	s_mov_b32 s14, s8
	s_mov_b64 s[18:19], s[12:13]
	s_mov_b64 s[16:17], s[10:11]
	s_waitcnt vmcnt(0)
	v_cvt_f32_f16_e32 v250, v246
	v_cvt_f32_f16_sdwa v251, v246 dst_sel:DWORD dst_unused:UNUSED_PAD src0_sel:WORD_1
	v_pk_fma_f32 v[168:169], v[168:169], v[100:101], v[250:251]
	s_nop 0
	v_cvt_pk_f16_f32 v246, v168, v169
	v_cvt_f32_f16_e32 v168, v248
	v_cvt_f32_f16_sdwa v169, v248 dst_sel:DWORD dst_unused:UNUSED_PAD src0_sel:WORD_1
	v_pk_fma_f32 v[164:165], v[164:165], v[96:97], v[168:169]
	s_nop 0
	v_cvt_pk_f16_f32 v248, v164, v165
	v_cvt_f32_f16_e32 v164, v247
	v_cvt_f32_f16_sdwa v165, v247 dst_sel:DWORD dst_unused:UNUSED_PAD src0_sel:WORD_1
	v_pk_fma_f32 v[164:165], v[170:171], v[102:103], v[164:165]
	s_nop 0
	v_cvt_pk_f16_f32 v247, v164, v165
	v_cvt_f32_f16_e32 v164, v249
	v_cvt_f32_f16_sdwa v165, v249 dst_sel:DWORD dst_unused:UNUSED_PAD src0_sel:WORD_1
	v_pk_fma_f32 v[164:165], v[166:167], v[98:99], v[164:165]
	s_nop 0
	v_cvt_pk_f16_f32 v249, v164, v165
	v_lshl_add_u64 v[164:165], s[0:1], 0, v[236:237]
	v_lshl_add_u64 v[168:169], v[164:165], 0, v[220:221]
	v_cvt_f32_f16_e32 v164, v200
	v_cvt_f32_f16_sdwa v165, v200 dst_sel:DWORD dst_unused:UNUSED_PAD src0_sel:WORD_1
	global_store_dwordx4 v[168:169], v[246:249], off
	v_pk_fma_f32 v[144:145], v[144:145], v[88:89], v[164:165]
	s_nop 0
	v_cvt_pk_f16_f32 v164, v144, v145
	v_cvt_f32_f16_e32 v144, v202
	v_cvt_f32_f16_sdwa v145, v202 dst_sel:DWORD dst_unused:UNUSED_PAD src0_sel:WORD_1
	v_pk_fma_f32 v[140:141], v[140:141], v[80:81], v[144:145]
	s_nop 0
	v_cvt_pk_f16_f32 v166, v140, v141
	v_cvt_f32_f16_e32 v140, v201
	v_cvt_f32_f16_sdwa v141, v201 dst_sel:DWORD dst_unused:UNUSED_PAD src0_sel:WORD_1
	v_pk_fma_f32 v[140:141], v[146:147], v[90:91], v[140:141]
	s_nop 0
	v_cvt_pk_f16_f32 v165, v140, v141
	v_cvt_f32_f16_e32 v140, v203
	v_cvt_f32_f16_sdwa v141, v203 dst_sel:DWORD dst_unused:UNUSED_PAD src0_sel:WORD_1
	v_pk_fma_f32 v[140:141], v[142:143], v[82:83], v[140:141]
	s_nop 0
	v_cvt_pk_f16_f32 v167, v140, v141
	v_cvt_f32_f16_e32 v140, v196
	v_cvt_f32_f16_sdwa v141, v196 dst_sel:DWORD dst_unused:UNUSED_PAD src0_sel:WORD_1
	global_store_dwordx4 v[168:169], v[164:167], off offset:256
	v_pk_fma_f32 v[128:129], v[128:129], v[100:101], v[140:141]
	s_nop 0
	v_cvt_pk_f16_f32 v140, v128, v129
	v_cvt_f32_f16_e32 v128, v198
	v_cvt_f32_f16_sdwa v129, v198 dst_sel:DWORD dst_unused:UNUSED_PAD src0_sel:WORD_1
	v_pk_fma_f32 v[124:125], v[124:125], v[96:97], v[128:129]
	s_nop 0
	v_cvt_pk_f16_f32 v142, v124, v125
	v_cvt_f32_f16_e32 v124, v197
	v_cvt_f32_f16_sdwa v125, v197 dst_sel:DWORD dst_unused:UNUSED_PAD src0_sel:WORD_1
	v_pk_fma_f32 v[124:125], v[130:131], v[102:103], v[124:125]
	s_nop 0
	v_cvt_pk_f16_f32 v141, v124, v125
	v_cvt_f32_f16_e32 v124, v199
	v_cvt_f32_f16_sdwa v125, v199 dst_sel:DWORD dst_unused:UNUSED_PAD src0_sel:WORD_1
	v_pk_fma_f32 v[124:125], v[126:127], v[98:99], v[124:125]
	s_nop 0
	v_cvt_pk_f16_f32 v143, v124, v125
	v_lshl_add_u64 v[124:125], s[0:1], 0, v[234:235]
	v_lshl_add_u64 v[128:129], v[124:125], 0, v[220:221]
	v_cvt_f32_f16_e32 v124, v192
	v_cvt_f32_f16_sdwa v125, v192 dst_sel:DWORD dst_unused:UNUSED_PAD src0_sel:WORD_1
	global_store_dwordx4 v[128:129], v[140:143], off
	v_pk_fma_f32 v[116:117], v[116:117], v[88:89], v[124:125]
	s_nop 0
	v_cvt_pk_f16_f32 v124, v116, v117
	v_cvt_f32_f16_e32 v116, v194
	v_cvt_f32_f16_sdwa v117, v194 dst_sel:DWORD dst_unused:UNUSED_PAD src0_sel:WORD_1
	v_pk_fma_f32 v[112:113], v[112:113], v[80:81], v[116:117]
	s_nop 0
	v_cvt_pk_f16_f32 v126, v112, v113
	v_cvt_f32_f16_e32 v112, v193
	v_cvt_f32_f16_sdwa v113, v193 dst_sel:DWORD dst_unused:UNUSED_PAD src0_sel:WORD_1
	v_pk_fma_f32 v[112:113], v[118:119], v[90:91], v[112:113]
	s_nop 0
	v_cvt_pk_f16_f32 v125, v112, v113
	v_cvt_f32_f16_e32 v112, v195
	v_cvt_f32_f16_sdwa v113, v195 dst_sel:DWORD dst_unused:UNUSED_PAD src0_sel:WORD_1
	v_pk_fma_f32 v[112:113], v[114:115], v[82:83], v[112:113]
	s_nop 0
	v_cvt_pk_f16_f32 v127, v112, v113
	v_cvt_f32_f16_e32 v112, v188
	v_cvt_f32_f16_sdwa v113, v188 dst_sel:DWORD dst_unused:UNUSED_PAD src0_sel:WORD_1
	global_store_dwordx4 v[128:129], v[124:127], off offset:256
	v_pk_fma_f32 v[108:109], v[108:109], v[100:101], v[112:113]
	s_nop 0
	v_cvt_pk_f16_f32 v112, v108, v109
	v_cvt_f32_f16_e32 v108, v190
	v_cvt_f32_f16_sdwa v109, v190 dst_sel:DWORD dst_unused:UNUSED_PAD src0_sel:WORD_1
	v_pk_fma_f32 v[104:105], v[104:105], v[96:97], v[108:109]
	s_nop 0
	v_cvt_pk_f16_f32 v114, v104, v105
	v_cvt_f32_f16_e32 v104, v189
	v_cvt_f32_f16_sdwa v105, v189 dst_sel:DWORD dst_unused:UNUSED_PAD src0_sel:WORD_1
	v_pk_fma_f32 v[104:105], v[110:111], v[102:103], v[104:105]
	s_nop 0
	v_cvt_pk_f16_f32 v113, v104, v105
	v_cvt_f32_f16_e32 v104, v191
	v_cvt_f32_f16_sdwa v105, v191 dst_sel:DWORD dst_unused:UNUSED_PAD src0_sel:WORD_1
	v_pk_fma_f32 v[104:105], v[106:107], v[98:99], v[104:105]
	s_nop 0
	v_cvt_pk_f16_f32 v115, v104, v105
	v_lshl_add_u64 v[104:105], s[0:1], 0, v[232:233]
	v_lshl_add_u64 v[108:109], v[104:105], 0, v[220:221]
	v_cvt_f32_f16_e32 v104, v184
	v_cvt_f32_f16_sdwa v105, v184 dst_sel:DWORD dst_unused:UNUSED_PAD src0_sel:WORD_1
	global_store_dwordx4 v[108:109], v[112:115], off
	v_pk_fma_f32 v[92:93], v[92:93], v[88:89], v[104:105]
	s_nop 0
	v_cvt_pk_f16_f32 v104, v92, v93
	v_cvt_f32_f16_e32 v92, v186
	v_cvt_f32_f16_sdwa v93, v186 dst_sel:DWORD dst_unused:UNUSED_PAD src0_sel:WORD_1
	v_pk_fma_f32 v[84:85], v[84:85], v[80:81], v[92:93]
	s_nop 0
	v_cvt_pk_f16_f32 v106, v84, v85
	v_cvt_f32_f16_e32 v84, v185
	v_cvt_f32_f16_sdwa v85, v185 dst_sel:DWORD dst_unused:UNUSED_PAD src0_sel:WORD_1
	v_pk_fma_f32 v[84:85], v[94:95], v[90:91], v[84:85]
	s_nop 0
	v_cvt_pk_f16_f32 v105, v84, v85
	v_cvt_f32_f16_e32 v84, v187
	v_cvt_f32_f16_sdwa v85, v187 dst_sel:DWORD dst_unused:UNUSED_PAD src0_sel:WORD_1
	v_pk_fma_f32 v[84:85], v[86:87], v[82:83], v[84:85]
	s_nop 0
	v_cvt_pk_f16_f32 v107, v84, v85
	v_cvt_f32_f16_e32 v84, v180
	v_cvt_f32_f16_sdwa v85, v180 dst_sel:DWORD dst_unused:UNUSED_PAD src0_sel:WORD_1
	global_store_dwordx4 v[108:109], v[104:107], off offset:256
	v_pk_fma_f32 v[76:77], v[76:77], v[100:101], v[84:85]
	s_nop 0
	v_cvt_pk_f16_f32 v84, v76, v77
	v_cvt_f32_f16_e32 v76, v182
	v_cvt_f32_f16_sdwa v77, v182 dst_sel:DWORD dst_unused:UNUSED_PAD src0_sel:WORD_1
	v_pk_fma_f32 v[72:73], v[72:73], v[96:97], v[76:77]
	s_nop 0
	v_cvt_pk_f16_f32 v86, v72, v73
	v_cvt_f32_f16_e32 v72, v181
	v_cvt_f32_f16_sdwa v73, v181 dst_sel:DWORD dst_unused:UNUSED_PAD src0_sel:WORD_1
	v_pk_fma_f32 v[72:73], v[78:79], v[102:103], v[72:73]
	s_nop 0
	v_cvt_pk_f16_f32 v85, v72, v73
	v_cvt_f32_f16_e32 v72, v183
	v_cvt_f32_f16_sdwa v73, v183 dst_sel:DWORD dst_unused:UNUSED_PAD src0_sel:WORD_1
	v_pk_fma_f32 v[72:73], v[74:75], v[98:99], v[72:73]
	s_nop 0
	v_cvt_pk_f16_f32 v87, v72, v73
	v_lshl_add_u64 v[72:73], s[0:1], 0, v[230:231]
	v_lshl_add_u64 v[76:77], v[72:73], 0, v[220:221]
	v_cvt_f32_f16_e32 v72, v176
	v_cvt_f32_f16_sdwa v73, v176 dst_sel:DWORD dst_unused:UNUSED_PAD src0_sel:WORD_1
	global_store_dwordx4 v[76:77], v[84:87], off
	v_pk_fma_f32 v[68:69], v[68:69], v[88:89], v[72:73]
	s_nop 0
	v_cvt_pk_f16_f32 v72, v68, v69
	v_cvt_f32_f16_e32 v68, v178
	v_cvt_f32_f16_sdwa v69, v178 dst_sel:DWORD dst_unused:UNUSED_PAD src0_sel:WORD_1
	v_pk_fma_f32 v[64:65], v[64:65], v[80:81], v[68:69]
	s_nop 0
	v_cvt_pk_f16_f32 v74, v64, v65
	v_cvt_f32_f16_e32 v64, v177
	v_cvt_f32_f16_sdwa v65, v177 dst_sel:DWORD dst_unused:UNUSED_PAD src0_sel:WORD_1
	v_pk_fma_f32 v[64:65], v[70:71], v[90:91], v[64:65]
	s_nop 0
	v_cvt_pk_f16_f32 v73, v64, v65
	v_cvt_f32_f16_e32 v64, v179
	v_cvt_f32_f16_sdwa v65, v179 dst_sel:DWORD dst_unused:UNUSED_PAD src0_sel:WORD_1
	v_pk_fma_f32 v[64:65], v[66:67], v[82:83], v[64:65]
	s_nop 0
	v_cvt_pk_f16_f32 v75, v64, v65
	v_cvt_f32_f16_e32 v64, v172
	v_cvt_f32_f16_sdwa v65, v172 dst_sel:DWORD dst_unused:UNUSED_PAD src0_sel:WORD_1
	global_store_dwordx4 v[76:77], v[72:75], off offset:256
	v_pk_fma_f32 v[60:61], v[60:61], v[100:101], v[64:65]
	s_nop 0
	v_cvt_pk_f16_f32 v64, v60, v61
	v_cvt_f32_f16_e32 v60, v174
	v_cvt_f32_f16_sdwa v61, v174 dst_sel:DWORD dst_unused:UNUSED_PAD src0_sel:WORD_1
	v_pk_fma_f32 v[56:57], v[56:57], v[96:97], v[60:61]
	s_nop 0
	v_cvt_pk_f16_f32 v66, v56, v57
	v_cvt_f32_f16_e32 v56, v173
	v_cvt_f32_f16_sdwa v57, v173 dst_sel:DWORD dst_unused:UNUSED_PAD src0_sel:WORD_1
	v_pk_fma_f32 v[56:57], v[62:63], v[102:103], v[56:57]
	s_nop 0
	v_cvt_pk_f16_f32 v65, v56, v57
	v_cvt_f32_f16_e32 v56, v175
	v_cvt_f32_f16_sdwa v57, v175 dst_sel:DWORD dst_unused:UNUSED_PAD src0_sel:WORD_1
	v_pk_fma_f32 v[56:57], v[58:59], v[98:99], v[56:57]
	s_nop 0
	v_cvt_pk_f16_f32 v67, v56, v57
	v_lshl_add_u64 v[56:57], s[0:1], 0, v[228:229]
	v_lshl_add_u64 v[60:61], v[56:57], 0, v[220:221]
	v_cvt_f32_f16_e32 v56, v160
	v_cvt_f32_f16_sdwa v57, v160 dst_sel:DWORD dst_unused:UNUSED_PAD src0_sel:WORD_1
	global_store_dwordx4 v[60:61], v[64:67], off
	v_pk_fma_f32 v[52:53], v[52:53], v[88:89], v[56:57]
	s_nop 0
	v_cvt_pk_f16_f32 v56, v52, v53
	v_cvt_f32_f16_e32 v52, v162
	v_cvt_f32_f16_sdwa v53, v162 dst_sel:DWORD dst_unused:UNUSED_PAD src0_sel:WORD_1
	v_pk_fma_f32 v[48:49], v[48:49], v[80:81], v[52:53]
	s_nop 0
	v_cvt_pk_f16_f32 v58, v48, v49
	v_cvt_f32_f16_e32 v48, v161
	v_cvt_f32_f16_sdwa v49, v161 dst_sel:DWORD dst_unused:UNUSED_PAD src0_sel:WORD_1
	v_pk_fma_f32 v[48:49], v[54:55], v[90:91], v[48:49]
	s_nop 0
	v_cvt_pk_f16_f32 v57, v48, v49
	v_cvt_f32_f16_e32 v48, v163
	v_cvt_f32_f16_sdwa v49, v163 dst_sel:DWORD dst_unused:UNUSED_PAD src0_sel:WORD_1
	v_pk_fma_f32 v[48:49], v[50:51], v[82:83], v[48:49]
	s_nop 0
	v_cvt_pk_f16_f32 v59, v48, v49
	v_cvt_f32_f16_e32 v48, v156
	v_cvt_f32_f16_sdwa v49, v156 dst_sel:DWORD dst_unused:UNUSED_PAD src0_sel:WORD_1
	global_store_dwordx4 v[60:61], v[56:59], off offset:256
	v_pk_fma_f32 v[44:45], v[44:45], v[100:101], v[48:49]
	s_nop 0
	v_cvt_pk_f16_f32 v48, v44, v45
	v_cvt_f32_f16_e32 v44, v158
	v_cvt_f32_f16_sdwa v45, v158 dst_sel:DWORD dst_unused:UNUSED_PAD src0_sel:WORD_1
	v_pk_fma_f32 v[40:41], v[40:41], v[96:97], v[44:45]
	s_nop 0
	v_cvt_pk_f16_f32 v50, v40, v41
	v_cvt_f32_f16_e32 v40, v157
	v_cvt_f32_f16_sdwa v41, v157 dst_sel:DWORD dst_unused:UNUSED_PAD src0_sel:WORD_1
	v_pk_fma_f32 v[40:41], v[46:47], v[102:103], v[40:41]
	s_nop 0
	v_cvt_pk_f16_f32 v49, v40, v41
	v_cvt_f32_f16_e32 v40, v159
	v_cvt_f32_f16_sdwa v41, v159 dst_sel:DWORD dst_unused:UNUSED_PAD src0_sel:WORD_1
	v_pk_fma_f32 v[40:41], v[42:43], v[98:99], v[40:41]
	s_nop 0
	v_cvt_pk_f16_f32 v51, v40, v41
	v_lshl_add_u64 v[40:41], s[0:1], 0, v[226:227]
	v_lshl_add_u64 v[44:45], v[40:41], 0, v[220:221]
	v_cvt_f32_f16_e32 v40, v152
	v_cvt_f32_f16_sdwa v41, v152 dst_sel:DWORD dst_unused:UNUSED_PAD src0_sel:WORD_1
	global_store_dwordx4 v[44:45], v[48:51], off
	v_pk_fma_f32 v[36:37], v[36:37], v[88:89], v[40:41]
	s_nop 0
	v_cvt_pk_f16_f32 v40, v36, v37
	v_cvt_f32_f16_e32 v36, v154
	v_cvt_f32_f16_sdwa v37, v154 dst_sel:DWORD dst_unused:UNUSED_PAD src0_sel:WORD_1
	v_pk_fma_f32 v[32:33], v[32:33], v[80:81], v[36:37]
	s_nop 0
	v_cvt_pk_f16_f32 v42, v32, v33
	v_cvt_f32_f16_e32 v32, v153
	v_cvt_f32_f16_sdwa v33, v153 dst_sel:DWORD dst_unused:UNUSED_PAD src0_sel:WORD_1
	v_pk_fma_f32 v[32:33], v[38:39], v[90:91], v[32:33]
	s_nop 0
	v_cvt_pk_f16_f32 v41, v32, v33
	v_cvt_f32_f16_e32 v32, v155
	v_cvt_f32_f16_sdwa v33, v155 dst_sel:DWORD dst_unused:UNUSED_PAD src0_sel:WORD_1
	v_pk_fma_f32 v[32:33], v[34:35], v[82:83], v[32:33]
	s_nop 0
	v_cvt_pk_f16_f32 v43, v32, v33
	v_cvt_f32_f16_e32 v32, v148
	v_cvt_f32_f16_sdwa v33, v148 dst_sel:DWORD dst_unused:UNUSED_PAD src0_sel:WORD_1
	global_store_dwordx4 v[44:45], v[40:43], off offset:256
	v_pk_fma_f32 v[28:29], v[28:29], v[100:101], v[32:33]
	s_nop 0
	v_cvt_pk_f16_f32 v32, v28, v29
	v_cvt_f32_f16_e32 v28, v150
	v_cvt_f32_f16_sdwa v29, v150 dst_sel:DWORD dst_unused:UNUSED_PAD src0_sel:WORD_1
	v_pk_fma_f32 v[24:25], v[24:25], v[96:97], v[28:29]
	s_nop 0
	v_cvt_pk_f16_f32 v34, v24, v25
	v_cvt_f32_f16_e32 v24, v149
	v_cvt_f32_f16_sdwa v25, v149 dst_sel:DWORD dst_unused:UNUSED_PAD src0_sel:WORD_1
	v_pk_fma_f32 v[24:25], v[30:31], v[102:103], v[24:25]
	s_nop 0
	v_cvt_pk_f16_f32 v33, v24, v25
	v_cvt_f32_f16_e32 v24, v151
	v_cvt_f32_f16_sdwa v25, v151 dst_sel:DWORD dst_unused:UNUSED_PAD src0_sel:WORD_1
	v_pk_fma_f32 v[24:25], v[26:27], v[98:99], v[24:25]
	s_nop 0
	v_cvt_pk_f16_f32 v35, v24, v25
	v_lshl_add_u64 v[24:25], s[0:1], 0, v[224:225]
	v_lshl_add_u64 v[28:29], v[24:25], 0, v[220:221]
	v_cvt_f32_f16_e32 v24, v136
	v_cvt_f32_f16_sdwa v25, v136 dst_sel:DWORD dst_unused:UNUSED_PAD src0_sel:WORD_1
	global_store_dwordx4 v[28:29], v[32:35], off
	v_pk_fma_f32 v[20:21], v[20:21], v[88:89], v[24:25]
	s_nop 0
	v_cvt_pk_f16_f32 v24, v20, v21
	v_cvt_f32_f16_e32 v20, v138
	v_cvt_f32_f16_sdwa v21, v138 dst_sel:DWORD dst_unused:UNUSED_PAD src0_sel:WORD_1
	v_pk_fma_f32 v[16:17], v[16:17], v[80:81], v[20:21]
	s_nop 0
	v_cvt_pk_f16_f32 v26, v16, v17
	v_cvt_f32_f16_e32 v16, v137
	v_cvt_f32_f16_sdwa v17, v137 dst_sel:DWORD dst_unused:UNUSED_PAD src0_sel:WORD_1
	v_pk_fma_f32 v[16:17], v[22:23], v[90:91], v[16:17]
	s_nop 0
	v_cvt_pk_f16_f32 v25, v16, v17
	v_cvt_f32_f16_e32 v16, v139
	v_cvt_f32_f16_sdwa v17, v139 dst_sel:DWORD dst_unused:UNUSED_PAD src0_sel:WORD_1
	v_pk_fma_f32 v[16:17], v[18:19], v[82:83], v[16:17]
	s_nop 0
	v_cvt_pk_f16_f32 v27, v16, v17
	v_cvt_f32_f16_e32 v16, v132
	v_cvt_f32_f16_sdwa v17, v132 dst_sel:DWORD dst_unused:UNUSED_PAD src0_sel:WORD_1
	global_store_dwordx4 v[28:29], v[24:27], off offset:256
	v_pk_fma_f32 v[12:13], v[12:13], v[100:101], v[16:17]
	s_nop 0
	v_cvt_pk_f16_f32 v16, v12, v13
	v_cvt_f32_f16_e32 v12, v134
	v_cvt_f32_f16_sdwa v13, v134 dst_sel:DWORD dst_unused:UNUSED_PAD src0_sel:WORD_1
	v_pk_fma_f32 v[8:9], v[8:9], v[96:97], v[12:13]
	s_nop 0
	v_cvt_pk_f16_f32 v18, v8, v9
	v_cvt_f32_f16_e32 v8, v133
	v_cvt_f32_f16_sdwa v9, v133 dst_sel:DWORD dst_unused:UNUSED_PAD src0_sel:WORD_1
	v_pk_fma_f32 v[8:9], v[14:15], v[102:103], v[8:9]
	s_nop 0
	v_cvt_pk_f16_f32 v17, v8, v9
	v_cvt_f32_f16_e32 v8, v135
	v_cvt_f32_f16_sdwa v9, v135 dst_sel:DWORD dst_unused:UNUSED_PAD src0_sel:WORD_1
	v_pk_fma_f32 v[8:9], v[10:11], v[98:99], v[8:9]
	s_nop 0
	v_cvt_pk_f16_f32 v19, v8, v9
	v_lshl_add_u64 v[8:9], s[0:1], 0, v[222:223]
	v_lshl_add_u64 v[12:13], v[8:9], 0, v[220:221]
	v_cvt_f32_f16_e32 v8, v120
	v_cvt_f32_f16_sdwa v9, v120 dst_sel:DWORD dst_unused:UNUSED_PAD src0_sel:WORD_1
	global_store_dwordx4 v[12:13], v[16:19], off
	v_pk_fma_f32 v[4:5], v[4:5], v[88:89], v[8:9]
	s_nop 0
	v_cvt_pk_f16_f32 v8, v4, v5
	v_cvt_f32_f16_e32 v4, v122
	v_cvt_f32_f16_sdwa v5, v122 dst_sel:DWORD dst_unused:UNUSED_PAD src0_sel:WORD_1
	v_pk_fma_f32 v[0:1], v[0:1], v[80:81], v[4:5]
	s_nop 0
	v_cvt_pk_f16_f32 v10, v0, v1
	v_cvt_f32_f16_e32 v0, v121
	v_cvt_f32_f16_sdwa v1, v121 dst_sel:DWORD dst_unused:UNUSED_PAD src0_sel:WORD_1
	v_pk_fma_f32 v[0:1], v[6:7], v[90:91], v[0:1]
	s_nop 0
	v_cvt_pk_f16_f32 v9, v0, v1
	v_cvt_f32_f16_e32 v0, v123
	v_cvt_f32_f16_sdwa v1, v123 dst_sel:DWORD dst_unused:UNUSED_PAD src0_sel:WORD_1
	v_pk_fma_f32 v[0:1], v[2:3], v[82:83], v[0:1]
	s_nop 0
	v_cvt_pk_f16_f32 v11, v0, v1
	global_store_dwordx4 v[12:13], v[8:11], off offset:256
	s_cbranch_vccz .LBB0_640
	s_waitcnt vmcnt(0)
	s_cmpk_gt_u32 s22, 0xff
	s_cbranch_scc1 .LBB0_651
	s_barrier

.LBB0_1185:
	ds_read_b128 v[88:91], v243
	ds_read_b128 v[96:99], v243 offset:1024
	ds_read_b128 v[108:111], v243 offset:2048
	ds_read_b128 v[116:119], v243 offset:3072
	s_add_u32 s26, s24, 0xfff80080
	s_addc_u32 s27, s25, -1
	s_cmp_eq_u32 s64, 28
	s_cselect_b32 s29, s17, s27
	s_cselect_b32 s28, s31, s26
	s_cselect_b32 s27, s15, s63
	s_cselect_b32 s26, s61, s62
	v_lshl_add_u64 v[176:177], s[24:25], 0, v[212:213]
	s_add_i32 m0, s23, 0xc000
	ds_read_b128 v[128:131], v244
	ds_read_b128 v[136:139], v244 offset:1024
	ds_read_b128 v[144:147], v244 offset:2048
	ds_read_b128 v[148:151], v244 offset:3072
	ds_read_b128 v[152:155], v244 offset:4096
	ds_read_b128 v[164:167], v244 offset:5120
	ds_read_b128 v[168:171], v244 offset:6144
	ds_read_b128 v[172:175], v244 offset:7168
	global_load_lds_dwordx4 v[176:177], off
	v_lshl_add_u64 v[176:177], s[24:25], 0, v[214:215]
	s_add_i32 m0, s23, 0xe000
	s_nop 0
	global_load_lds_dwordx4 v[176:177], off
	s_waitcnt lgkmcnt(8)
	s_barrier
	s_waitcnt lgkmcnt(0)
	v_mfma_f32_16x16x32_f16 v[160:163], v[88:91], v[128:131], v[160:163]
	v_mfma_f32_16x16x32_f16 v[156:159], v[108:111], v[128:131], v[156:159]
	v_mfma_f32_16x16x32_f16 v[124:127], v[88:91], v[144:147], v[124:127]
	v_mfma_f32_16x16x32_f16 v[120:123], v[108:111], v[144:147], v[120:123]
	v_mfma_f32_16x16x32_f16 v[100:103], v[88:91], v[152:155], v[100:103]
	v_mfma_f32_16x16x32_f16 v[92:95], v[108:111], v[152:155], v[92:95]
	v_mfma_f32_16x16x32_f16 v[76:79], v[88:91], v[168:171], v[76:79]
	v_mfma_f32_16x16x32_f16 v[72:75], v[108:111], v[168:171], v[72:75]
	v_mfma_f32_16x16x32_f16 v[160:163], v[96:99], v[136:139], v[160:163]
	v_mfma_f32_16x16x32_f16 v[156:159], v[116:119], v[136:139], v[156:159]
	v_mfma_f32_16x16x32_f16 v[124:127], v[96:99], v[148:151], v[124:127]
	v_mfma_f32_16x16x32_f16 v[120:123], v[116:119], v[148:151], v[120:123]
	v_mfma_f32_16x16x32_f16 v[100:103], v[96:99], v[164:167], v[100:103]
	v_mfma_f32_16x16x32_f16 v[92:95], v[116:119], v[164:167], v[92:95]
	v_mfma_f32_16x16x32_f16 v[76:79], v[96:99], v[172:175], v[76:79]
	v_mfma_f32_16x16x32_f16 v[72:75], v[116:119], v[172:175], v[72:75]
	s_barrier
	s_add_i32 s65, s59, s44
	v_lshl_add_u64 v[192:193], s[26:27], 0, v[206:207]
	s_mov_b32 m0, s65
	ds_read_b128 v[176:179], v245
	ds_read_b128 v[180:183], v245 offset:1024
	ds_read_b128 v[184:187], v245 offset:2048
	ds_read_b128 v[188:191], v245 offset:3072
	global_load_lds_dwordx4 v[192:193], off
	v_lshl_add_u64 v[194:195], s[26:27], 0, v[210:211]
	s_add_i32 m0, s65, 0x2000
	s_nop 0
	global_load_lds_dwordx4 v[194:195], off
	s_barrier
	s_waitcnt lgkmcnt(0)
	v_mfma_f32_16x16x32_f16 v[140:143], v[176:179], v[128:131], v[140:143]
	v_mfma_f32_16x16x32_f16 v[112:115], v[176:179], v[144:147], v[112:115]
	v_mfma_f32_16x16x32_f16 v[104:107], v[184:187], v[144:147], v[104:107]
	v_mfma_f32_16x16x32_f16 v[84:87], v[176:179], v[152:155], v[84:87]
	v_mfma_f32_16x16x32_f16 v[80:83], v[184:187], v[152:155], v[80:83]
	v_mfma_f32_16x16x32_f16 v[68:71], v[176:179], v[168:171], v[68:71]
	v_mfma_f32_16x16x32_f16 v[64:67], v[184:187], v[168:171], v[64:67]
	v_mfma_f32_16x16x32_f16 v[140:143], v[180:183], v[136:139], v[140:143]
	v_mfma_f32_16x16x32_f16 v[128:131], v[184:187], v[128:131], v[132:135]
	v_mfma_f32_16x16x32_f16 v[112:115], v[180:183], v[148:151], v[112:115]
	v_mfma_f32_16x16x32_f16 v[104:107], v[188:191], v[148:151], v[104:107]
	v_mfma_f32_16x16x32_f16 v[84:87], v[180:183], v[164:167], v[84:87]
	v_mfma_f32_16x16x32_f16 v[80:83], v[188:191], v[164:167], v[80:83]
	v_mfma_f32_16x16x32_f16 v[68:71], v[180:183], v[172:175], v[68:71]
	v_mfma_f32_16x16x32_f16 v[64:67], v[188:191], v[172:175], v[64:67]
	v_mfma_f32_16x16x32_f16 v[128:131], v[188:191], v[136:139], v[128:131]
	s_barrier
	s_mov_b32 m0, s23
	v_lshl_add_u64 v[196:197], s[28:29], 0, v[204:205]
	ds_read_b128 v[132:135], v244 offset:16384
	ds_read_b128 v[136:139], v244 offset:17408
	ds_read_b128 v[144:147], v244 offset:18432
	ds_read_b128 v[148:151], v244 offset:19456
	ds_read_b128 v[152:155], v244 offset:20480
	ds_read_b128 v[164:167], v244 offset:21504
	ds_read_b128 v[168:171], v244 offset:22528
	ds_read_b128 v[172:175], v244 offset:23552
	global_load_lds_dwordx4 v[196:197], off
	v_lshl_add_u64 v[198:199], s[28:29], 0, v[208:209]
	s_mov_b32 m0, s45
	s_nop 0
	global_load_lds_dwordx4 v[198:199], off
	s_barrier
	s_waitcnt lgkmcnt(0)
	v_mfma_f32_16x16x32_f16 v[60:63], v[88:91], v[132:135], v[60:63]
	v_mfma_f32_16x16x32_f16 v[56:59], v[108:111], v[132:135], v[56:59]
	v_mfma_f32_16x16x32_f16 v[44:47], v[88:91], v[144:147], v[44:47]
	v_mfma_f32_16x16x32_f16 v[40:43], v[108:111], v[144:147], v[40:43]
	v_mfma_f32_16x16x32_f16 v[28:31], v[88:91], v[152:155], v[28:31]
	v_mfma_f32_16x16x32_f16 v[24:27], v[108:111], v[152:155], v[24:27]
	v_mfma_f32_16x16x32_f16 v[12:15], v[88:91], v[168:171], v[12:15]
	v_mfma_f32_16x16x32_f16 v[8:11], v[108:111], v[168:171], v[8:11]
	v_mfma_f32_16x16x32_f16 v[60:63], v[96:99], v[136:139], v[60:63]
	v_mfma_f32_16x16x32_f16 v[56:59], v[116:119], v[136:139], v[56:59]
	v_mfma_f32_16x16x32_f16 v[44:47], v[96:99], v[148:151], v[44:47]
	v_mfma_f32_16x16x32_f16 v[40:43], v[116:119], v[148:151], v[40:43]
	v_mfma_f32_16x16x32_f16 v[28:31], v[96:99], v[164:167], v[28:31]
	v_mfma_f32_16x16x32_f16 v[24:27], v[116:119], v[164:167], v[24:27]
	v_mfma_f32_16x16x32_f16 v[12:15], v[96:99], v[172:175], v[12:15]
	v_mfma_f32_16x16x32_f16 v[8:11], v[116:119], v[172:175], v[8:11]
	s_barrier
	s_add_u32 s66, s26, 0x80000
	s_addc_u32 s67, s27, 0
	s_add_i32 s65, s60, s44
	v_lshl_add_u64 v[88:89], s[66:67], 0, v[206:207]
	s_mov_b32 m0, s65
	s_nop 0
	global_load_lds_dwordx4 v[88:89], off
	v_lshl_add_u64 v[88:89], s[66:67], 0, v[210:211]
	s_add_i32 m0, s65, 0x2000
	s_nop 0
	global_load_lds_dwordx4 v[88:89], off
	s_waitcnt vmcnt(6)
	s_barrier
	v_mfma_f32_16x16x32_f16 v[52:55], v[176:179], v[132:135], v[52:55]
	v_mfma_f32_16x16x32_f16 v[48:51], v[184:187], v[132:135], v[48:51]
	v_mfma_f32_16x16x32_f16 v[36:39], v[176:179], v[144:147], v[36:39]
	v_mfma_f32_16x16x32_f16 v[32:35], v[184:187], v[144:147], v[32:35]
	v_mfma_f32_16x16x32_f16 v[20:23], v[176:179], v[152:155], v[20:23]
	v_mfma_f32_16x16x32_f16 v[16:19], v[184:187], v[152:155], v[16:19]
	v_mfma_f32_16x16x32_f16 v[4:7], v[176:179], v[168:171], v[4:7]
	v_mfma_f32_16x16x32_f16 v[0:3], v[184:187], v[168:171], v[0:3]
	v_mfma_f32_16x16x32_f16 v[52:55], v[180:183], v[136:139], v[52:55]
	v_mfma_f32_16x16x32_f16 v[48:51], v[188:191], v[136:139], v[48:51]
	v_mfma_f32_16x16x32_f16 v[36:39], v[180:183], v[148:151], v[36:39]
	v_mfma_f32_16x16x32_f16 v[32:35], v[188:191], v[148:151], v[32:35]
	v_mfma_f32_16x16x32_f16 v[20:23], v[180:183], v[164:167], v[20:23]
	v_mfma_f32_16x16x32_f16 v[16:19], v[188:191], v[164:167], v[16:19]
	v_mfma_f32_16x16x32_f16 v[4:7], v[180:183], v[172:175], v[4:7]
	v_mfma_f32_16x16x32_f16 v[0:3], v[188:191], v[172:175], v[0:3]
	s_barrier
	s_add_i32 s65, 0, 0x18000
	v_add_u32_e32 v116, s65, v241
	ds_read_b128 v[88:91], v116
	ds_read_b128 v[96:99], v116 offset:1024
	ds_read_b128 v[108:111], v116 offset:2048
	ds_read_b128 v[116:119], v116 offset:3072
	s_add_u32 s28, s28, 0x80000
	s_addc_u32 s29, s29, 0
	s_mov_b32 m0, s48
	v_lshl_add_u64 v[176:177], s[28:29], 0, v[204:205]
	ds_read_b128 v[132:135], v244 offset:32768
	ds_read_b128 v[136:139], v244 offset:33792
	ds_read_b128 v[144:147], v244 offset:34816
	ds_read_b128 v[148:151], v244 offset:35840
	ds_read_b128 v[152:155], v244 offset:36864
	ds_read_b128 v[164:167], v244 offset:37888
	ds_read_b128 v[168:171], v244 offset:38912
	ds_read_b128 v[172:175], v244 offset:39936
	global_load_lds_dwordx4 v[176:177], off
	v_lshl_add_u64 v[176:177], s[28:29], 0, v[208:209]
	s_mov_b32 m0, s49
	s_nop 0
	global_load_lds_dwordx4 v[176:177], off
	s_waitcnt lgkmcnt(8)
	s_barrier
	s_waitcnt lgkmcnt(0)
	v_mfma_f32_16x16x32_f16 v[160:163], v[88:91], v[132:135], v[160:163]
	v_mfma_f32_16x16x32_f16 v[156:159], v[108:111], v[132:135], v[156:159]
	v_mfma_f32_16x16x32_f16 v[124:127], v[88:91], v[144:147], v[124:127]
	v_mfma_f32_16x16x32_f16 v[120:123], v[108:111], v[144:147], v[120:123]
	v_mfma_f32_16x16x32_f16 v[100:103], v[88:91], v[152:155], v[100:103]
	v_mfma_f32_16x16x32_f16 v[92:95], v[108:111], v[152:155], v[92:95]
	v_mfma_f32_16x16x32_f16 v[76:79], v[88:91], v[168:171], v[76:79]
	v_mfma_f32_16x16x32_f16 v[72:75], v[108:111], v[168:171], v[72:75]
	v_mfma_f32_16x16x32_f16 v[160:163], v[96:99], v[136:139], v[160:163]
	v_mfma_f32_16x16x32_f16 v[156:159], v[116:119], v[136:139], v[156:159]
	v_mfma_f32_16x16x32_f16 v[124:127], v[96:99], v[148:151], v[124:127]
	v_mfma_f32_16x16x32_f16 v[120:123], v[116:119], v[148:151], v[120:123]
	v_mfma_f32_16x16x32_f16 v[100:103], v[96:99], v[164:167], v[100:103]
	v_mfma_f32_16x16x32_f16 v[92:95], v[116:119], v[164:167], v[92:95]
	v_mfma_f32_16x16x32_f16 v[76:79], v[96:99], v[172:175], v[76:79]
	v_mfma_f32_16x16x32_f16 v[72:75], v[116:119], v[172:175], v[72:75]
	s_barrier
	s_add_i32 s28, 0, 0x1c000
	s_add_i32 s29, s65, s44
	v_add_u32_e32 v188, s28, v241
	v_lshl_add_u64 v[192:193], v[192:193], 0, s[6:7]
	s_mov_b32 m0, s29
	ds_read_b128 v[176:179], v188
	ds_read_b128 v[180:183], v188 offset:1024
	ds_read_b128 v[184:187], v188 offset:2048
	ds_read_b128 v[188:191], v188 offset:3072
	global_load_lds_dwordx4 v[192:193], off
	v_lshl_add_u64 v[192:193], v[194:195], 0, s[6:7]
	s_add_i32 m0, s29, 0x2000
	s_nop 0
	global_load_lds_dwordx4 v[192:193], off
	s_barrier
	s_waitcnt lgkmcnt(0)
	v_mfma_f32_16x16x32_f16 v[140:143], v[176:179], v[132:135], v[140:143]
	v_mfma_f32_16x16x32_f16 v[128:131], v[184:187], v[132:135], v[128:131]
	v_mfma_f32_16x16x32_f16 v[112:115], v[176:179], v[144:147], v[112:115]
	v_mfma_f32_16x16x32_f16 v[104:107], v[184:187], v[144:147], v[104:107]
	v_mfma_f32_16x16x32_f16 v[84:87], v[176:179], v[152:155], v[84:87]
	v_mfma_f32_16x16x32_f16 v[80:83], v[184:187], v[152:155], v[80:83]
	v_mfma_f32_16x16x32_f16 v[68:71], v[176:179], v[168:171], v[68:71]
	v_mfma_f32_16x16x32_f16 v[64:67], v[184:187], v[168:171], v[64:67]
	v_mfma_f32_16x16x32_f16 v[140:143], v[180:183], v[136:139], v[140:143]
	v_mfma_f32_16x16x32_f16 v[132:135], v[188:191], v[136:139], v[128:131]
	v_mfma_f32_16x16x32_f16 v[112:115], v[180:183], v[148:151], v[112:115]
	v_mfma_f32_16x16x32_f16 v[104:107], v[188:191], v[148:151], v[104:107]
	v_mfma_f32_16x16x32_f16 v[84:87], v[180:183], v[164:167], v[84:87]
	v_mfma_f32_16x16x32_f16 v[80:83], v[188:191], v[164:167], v[80:83]
	v_mfma_f32_16x16x32_f16 v[68:71], v[180:183], v[172:175], v[68:71]
	v_mfma_f32_16x16x32_f16 v[64:67], v[188:191], v[172:175], v[64:67]
	s_barrier
	s_mov_b32 m0, s51
	v_lshl_add_u64 v[192:193], v[196:197], 0, s[6:7]
	ds_read_b128 v[128:131], v244 offset:49152
	ds_read_b128 v[136:139], v244 offset:50176
	ds_read_b128 v[144:147], v244 offset:51200
	ds_read_b128 v[148:151], v244 offset:52224
	ds_read_b128 v[152:155], v244 offset:53248
	ds_read_b128 v[164:167], v244 offset:54272
	ds_read_b128 v[168:171], v244 offset:55296
	ds_read_b128 v[172:175], v244 offset:56320
	global_load_lds_dwordx4 v[192:193], off
	v_lshl_add_u64 v[192:193], v[198:199], 0, s[6:7]
	s_mov_b32 m0, s54
	s_nop 0
	global_load_lds_dwordx4 v[192:193], off
	s_barrier
	s_waitcnt lgkmcnt(0)
	v_mfma_f32_16x16x32_f16 v[60:63], v[88:91], v[128:131], v[60:63]
	v_mfma_f32_16x16x32_f16 v[56:59], v[108:111], v[128:131], v[56:59]
	v_mfma_f32_16x16x32_f16 v[44:47], v[88:91], v[144:147], v[44:47]
	v_mfma_f32_16x16x32_f16 v[40:43], v[108:111], v[144:147], v[40:43]
	v_mfma_f32_16x16x32_f16 v[28:31], v[88:91], v[152:155], v[28:31]
	v_mfma_f32_16x16x32_f16 v[24:27], v[108:111], v[152:155], v[24:27]
	v_mfma_f32_16x16x32_f16 v[12:15], v[88:91], v[168:171], v[12:15]
	v_mfma_f32_16x16x32_f16 v[8:11], v[108:111], v[168:171], v[8:11]
	v_mfma_f32_16x16x32_f16 v[60:63], v[96:99], v[136:139], v[60:63]
	v_mfma_f32_16x16x32_f16 v[56:59], v[116:119], v[136:139], v[56:59]
	v_mfma_f32_16x16x32_f16 v[44:47], v[96:99], v[148:151], v[44:47]
	v_mfma_f32_16x16x32_f16 v[40:43], v[116:119], v[148:151], v[40:43]
	v_mfma_f32_16x16x32_f16 v[28:31], v[96:99], v[164:167], v[28:31]
	v_mfma_f32_16x16x32_f16 v[24:27], v[116:119], v[164:167], v[24:27]
	v_mfma_f32_16x16x32_f16 v[12:15], v[96:99], v[172:175], v[12:15]
	v_mfma_f32_16x16x32_f16 v[8:11], v[116:119], v[172:175], v[8:11]
	s_barrier
	s_add_u32 s26, s26, 0x80080
	s_addc_u32 s27, s27, 0
	s_add_i32 s28, s28, s44
	v_lshl_add_u64 v[88:89], s[26:27], 0, v[206:207]
	s_mov_b32 m0, s28
	s_nop 0
	global_load_lds_dwordx4 v[88:89], off
	v_lshl_add_u64 v[88:89], s[26:27], 0, v[210:211]
	s_add_i32 m0, s28, 0x2000
	s_nop 0
	global_load_lds_dwordx4 v[88:89], off
	s_waitcnt vmcnt(6)
	s_barrier
	v_mfma_f32_16x16x32_f16 v[52:55], v[176:179], v[128:131], v[52:55]
	v_mfma_f32_16x16x32_f16 v[48:51], v[184:187], v[128:131], v[48:51]
	v_mfma_f32_16x16x32_f16 v[36:39], v[176:179], v[144:147], v[36:39]
	v_mfma_f32_16x16x32_f16 v[32:35], v[184:187], v[144:147], v[32:35]
	v_mfma_f32_16x16x32_f16 v[20:23], v[176:179], v[152:155], v[20:23]
	v_mfma_f32_16x16x32_f16 v[16:19], v[184:187], v[152:155], v[16:19]
	v_mfma_f32_16x16x32_f16 v[4:7], v[176:179], v[168:171], v[4:7]
	v_mfma_f32_16x16x32_f16 v[0:3], v[184:187], v[168:171], v[0:3]
	v_mfma_f32_16x16x32_f16 v[52:55], v[180:183], v[136:139], v[52:55]
	v_mfma_f32_16x16x32_f16 v[48:51], v[188:191], v[136:139], v[48:51]
	v_mfma_f32_16x16x32_f16 v[36:39], v[180:183], v[148:151], v[36:39]
	v_mfma_f32_16x16x32_f16 v[32:35], v[188:191], v[148:151], v[32:35]
	v_mfma_f32_16x16x32_f16 v[20:23], v[180:183], v[164:167], v[20:23]
	v_mfma_f32_16x16x32_f16 v[16:19], v[188:191], v[164:167], v[16:19]
	v_mfma_f32_16x16x32_f16 v[4:7], v[180:183], v[172:175], v[4:7]
	v_mfma_f32_16x16x32_f16 v[0:3], v[188:191], v[172:175], v[0:3]
	s_barrier
	s_add_i32 s64, s64, 2
	s_add_u32 s24, s24, 0x100
	s_addc_u32 s25, s25, 0
	s_add_u32 s62, s62, 0x100
	s_addc_u32 s63, s63, 0
	s_cmp_gt_u32 s64, 29
	s_cbranch_scc0 .LBB0_1185
	s_setprio 0
	s_lshl_b32 s15, s22, 8
	s_add_i32 s17, s15, 0xffffe000
	s_lshr_b32 s17, s17, 11
	s_mulk_i32 s17, 0x1800
	s_addk_i32 s17, 0x1800
	s_cmp_gt_i32 s22, 31
	s_cselect_b32 s24, s17, 0
	s_ashr_i32 s25, s24, 31
	v_lshl_or_b32 v128, s30, 8, v242
	s_lshl_b64 s[24:25], s[24:25], 2
	s_add_u32 s24, s42, s24
	v_ashrrev_i32_e32 v129, 31, v128
	v_add_u32_e32 v130, s15, v240
	s_addc_u32 s25, s43, s25
	v_lshlrev_b64 v[220:221], 1, v[128:129]
	v_ashrrev_i32_e32 v131, 31, v130
	v_lshl_add_u64 v[96:97], v[128:129], 2, s[24:25]
	v_lshl_add_u64 v[128:129], s[4:5], 0, v[220:221]
	v_lshlrev_b64 v[236:237], 12, v[130:131]
	v_lshl_add_u64 v[136:137], v[128:129], 0, v[236:237]
	global_load_dwordx4 v[108:111], v[96:97], off offset:16
	global_load_dwordx4 v[116:119], v[96:97], off
	global_load_dwordx4 v[88:91], v[96:97], off offset:528
	s_nop 0
	global_load_dwordx4 v[96:99], v[96:97], off offset:512
	s_nop 0
	global_load_dwordx4 v[246:249], v[136:137], off nt
	global_load_dwordx4 v[200:203], v[136:137], off offset:256 nt
	v_or_b32_e32 v136, 16, v130
	v_ashrrev_i32_e32 v137, 31, v136
	v_lshlrev_b64 v[234:235], 12, v[136:137]
	v_lshl_add_u64 v[136:137], v[128:129], 0, v[234:235]
	global_load_dwordx4 v[196:199], v[136:137], off nt
	global_load_dwordx4 v[192:195], v[136:137], off offset:256 nt
	v_or_b32_e32 v136, 32, v130
	v_ashrrev_i32_e32 v137, 31, v136
	v_lshlrev_b64 v[232:233], 12, v[136:137]
	v_lshl_add_u64 v[136:137], v[128:129], 0, v[232:233]
	global_load_dwordx4 v[188:191], v[136:137], off nt
	global_load_dwordx4 v[184:187], v[136:137], off offset:256 nt
	v_readlane_b32 s64, v254, 21
	v_readlane_b32 s68, v254, 25
	v_readlane_b32 s69, v254, 26
	s_mov_b64 s[56:57], s[68:69]
	v_or_b32_e32 v130, 48, v130
	v_ashrrev_i32_e32 v131, 31, v130
	v_lshlrev_b64 v[230:231], 12, v[130:131]
	v_lshl_add_u64 v[130:131], v[128:129], 0, v[230:231]
	global_load_dwordx4 v[180:183], v[130:131], off nt
	global_load_dwordx4 v[176:179], v[130:131], off offset:256 nt
	v_lshl_add_u64 v[228:229], v[236:237], 0, s[0:1]
	v_lshl_add_u64 v[130:131], v[128:129], 0, v[228:229]
	global_load_dwordx4 v[172:175], v[130:131], off nt
	global_load_dwordx4 v[168:171], v[130:131], off offset:256 nt
	v_lshl_add_u64 v[226:227], v[236:237], 0, s[8:9]
	v_lshl_add_u64 v[130:131], v[128:129], 0, v[226:227]
	global_load_dwordx4 v[164:167], v[130:131], off nt
	global_load_dwordx4 v[152:155], v[130:131], off offset:256 nt
	v_lshl_add_u64 v[224:225], v[236:237], 0, s[10:11]
	v_lshl_add_u64 v[130:131], v[128:129], 0, v[224:225]
	global_load_dwordx4 v[148:151], v[130:131], off nt
	global_load_dwordx4 v[144:147], v[130:131], off offset:256 nt
	v_lshl_add_u64 v[222:223], v[236:237], 0, s[12:13]
	v_lshl_add_u64 v[128:129], v[128:129], 0, v[222:223]
	global_load_dwordx4 v[136:139], v[128:129], off nt
	s_nop 0
	global_load_dwordx4 v[128:131], v[128:129], off offset:256 nt
	s_and_b64 vcc, exec, s[2:3]
	s_mov_b32 s30, s14
	s_mov_b32 s22, s16
	s_mov_b64 s[26:27], s[20:21]
	s_mov_b64 s[24:25], s[18:19]
	v_readlane_b32 s65, v254, 22
	v_readlane_b32 s66, v254, 23
	v_readlane_b32 s67, v254, 24
	v_readlane_b32 s70, v254, 27
	v_readlane_b32 s71, v254, 28
	v_readlane_b32 s72, v254, 29
	v_readlane_b32 s73, v254, 30
	v_readlane_b32 s74, v254, 31
	v_readlane_b32 s75, v254, 32
	v_readlane_b32 s76, v254, 33
	v_readlane_b32 s77, v254, 34
	v_readlane_b32 s78, v254, 35
	v_readlane_b32 s79, v254, 36
	s_waitcnt vmcnt(0)
	v_cvt_f32_f16_e32 v250, v246
	v_cvt_f32_f16_sdwa v251, v246 dst_sel:DWORD dst_unused:UNUSED_PAD src0_sel:WORD_1
	v_pk_fma_f32 v[160:161], v[160:161], v[116:117], v[250:251]
	s_nop 0
	v_cvt_pk_f16_f32 v246, v160, v161
	v_cvt_f32_f16_e32 v160, v248
	v_cvt_f32_f16_sdwa v161, v248 dst_sel:DWORD dst_unused:UNUSED_PAD src0_sel:WORD_1
	v_pk_fma_f32 v[156:157], v[156:157], v[108:109], v[160:161]
	s_nop 0
	v_cvt_pk_f16_f32 v248, v156, v157
	v_cvt_f32_f16_e32 v156, v247
	v_cvt_f32_f16_sdwa v157, v247 dst_sel:DWORD dst_unused:UNUSED_PAD src0_sel:WORD_1
	v_pk_fma_f32 v[156:157], v[162:163], v[118:119], v[156:157]
	s_nop 0
	v_cvt_pk_f16_f32 v247, v156, v157
	v_cvt_f32_f16_e32 v156, v249
	v_cvt_f32_f16_sdwa v157, v249 dst_sel:DWORD dst_unused:UNUSED_PAD src0_sel:WORD_1
	v_pk_fma_f32 v[156:157], v[158:159], v[110:111], v[156:157]
	s_nop 0
	v_cvt_pk_f16_f32 v249, v156, v157
	v_lshl_add_u64 v[156:157], s[56:57], 0, v[236:237]
	v_lshl_add_u64 v[160:161], v[156:157], 0, v[220:221]
	v_cvt_f32_f16_e32 v156, v200
	v_cvt_f32_f16_sdwa v157, v200 dst_sel:DWORD dst_unused:UNUSED_PAD src0_sel:WORD_1
	global_store_dwordx4 v[160:161], v[246:249], off
	v_pk_fma_f32 v[140:141], v[140:141], v[96:97], v[156:157]
	s_nop 0
	v_cvt_pk_f16_f32 v156, v140, v141
	v_cvt_f32_f16_e32 v140, v202
	v_cvt_f32_f16_sdwa v141, v202 dst_sel:DWORD dst_unused:UNUSED_PAD src0_sel:WORD_1
	v_pk_fma_f32 v[132:133], v[132:133], v[88:89], v[140:141]
	s_nop 0
	v_cvt_pk_f16_f32 v158, v132, v133
	v_cvt_f32_f16_e32 v132, v201
	v_cvt_f32_f16_sdwa v133, v201 dst_sel:DWORD dst_unused:UNUSED_PAD src0_sel:WORD_1
	v_pk_fma_f32 v[132:133], v[142:143], v[98:99], v[132:133]
	s_nop 0
	v_cvt_pk_f16_f32 v157, v132, v133
	v_cvt_f32_f16_e32 v132, v203
	v_cvt_f32_f16_sdwa v133, v203 dst_sel:DWORD dst_unused:UNUSED_PAD src0_sel:WORD_1
	v_pk_fma_f32 v[132:133], v[134:135], v[90:91], v[132:133]
	s_nop 0
	v_cvt_pk_f16_f32 v159, v132, v133
	v_cvt_f32_f16_e32 v132, v196
	v_cvt_f32_f16_sdwa v133, v196 dst_sel:DWORD dst_unused:UNUSED_PAD src0_sel:WORD_1
	global_store_dwordx4 v[160:161], v[156:159], off offset:256
	v_pk_fma_f32 v[124:125], v[124:125], v[116:117], v[132:133]
	s_nop 0
	v_cvt_pk_f16_f32 v132, v124, v125
	v_cvt_f32_f16_e32 v124, v198
	v_cvt_f32_f16_sdwa v125, v198 dst_sel:DWORD dst_unused:UNUSED_PAD src0_sel:WORD_1
	v_pk_fma_f32 v[120:121], v[120:121], v[108:109], v[124:125]
	s_nop 0
	v_cvt_pk_f16_f32 v134, v120, v121
	v_cvt_f32_f16_e32 v120, v197
	v_cvt_f32_f16_sdwa v121, v197 dst_sel:DWORD dst_unused:UNUSED_PAD src0_sel:WORD_1
	v_pk_fma_f32 v[120:121], v[126:127], v[118:119], v[120:121]
	s_nop 0
	v_cvt_pk_f16_f32 v133, v120, v121
	v_cvt_f32_f16_e32 v120, v199
	v_cvt_f32_f16_sdwa v121, v199 dst_sel:DWORD dst_unused:UNUSED_PAD src0_sel:WORD_1
	v_pk_fma_f32 v[120:121], v[122:123], v[110:111], v[120:121]
	s_nop 0
	v_cvt_pk_f16_f32 v135, v120, v121
	v_lshl_add_u64 v[120:121], s[56:57], 0, v[234:235]
	v_lshl_add_u64 v[124:125], v[120:121], 0, v[220:221]
	v_cvt_f32_f16_e32 v120, v192
	v_cvt_f32_f16_sdwa v121, v192 dst_sel:DWORD dst_unused:UNUSED_PAD src0_sel:WORD_1
	global_store_dwordx4 v[124:125], v[132:135], off
	v_pk_fma_f32 v[112:113], v[112:113], v[96:97], v[120:121]
	s_nop 0
	v_cvt_pk_f16_f32 v120, v112, v113
	v_cvt_f32_f16_e32 v112, v194
	v_cvt_f32_f16_sdwa v113, v194 dst_sel:DWORD dst_unused:UNUSED_PAD src0_sel:WORD_1
	v_pk_fma_f32 v[104:105], v[104:105], v[88:89], v[112:113]
	s_nop 0
	v_cvt_pk_f16_f32 v122, v104, v105
	v_cvt_f32_f16_e32 v104, v193
	v_cvt_f32_f16_sdwa v105, v193 dst_sel:DWORD dst_unused:UNUSED_PAD src0_sel:WORD_1
	v_pk_fma_f32 v[104:105], v[114:115], v[98:99], v[104:105]
	s_nop 0
	v_cvt_pk_f16_f32 v121, v104, v105
	v_cvt_f32_f16_e32 v104, v195
	v_cvt_f32_f16_sdwa v105, v195 dst_sel:DWORD dst_unused:UNUSED_PAD src0_sel:WORD_1
	v_pk_fma_f32 v[104:105], v[106:107], v[90:91], v[104:105]
	s_nop 0
	v_cvt_pk_f16_f32 v123, v104, v105
	v_cvt_f32_f16_e32 v104, v188
	v_cvt_f32_f16_sdwa v105, v188 dst_sel:DWORD dst_unused:UNUSED_PAD src0_sel:WORD_1
	global_store_dwordx4 v[124:125], v[120:123], off offset:256
	v_pk_fma_f32 v[100:101], v[100:101], v[116:117], v[104:105]
	s_nop 0
	v_cvt_pk_f16_f32 v104, v100, v101
	v_cvt_f32_f16_e32 v100, v190
	v_cvt_f32_f16_sdwa v101, v190 dst_sel:DWORD dst_unused:UNUSED_PAD src0_sel:WORD_1
	v_pk_fma_f32 v[92:93], v[92:93], v[108:109], v[100:101]
	s_nop 0
	v_cvt_pk_f16_f32 v106, v92, v93
	v_cvt_f32_f16_e32 v92, v189
	v_cvt_f32_f16_sdwa v93, v189 dst_sel:DWORD dst_unused:UNUSED_PAD src0_sel:WORD_1
	v_pk_fma_f32 v[92:93], v[102:103], v[118:119], v[92:93]
	s_nop 0
	v_cvt_pk_f16_f32 v105, v92, v93
	v_cvt_f32_f16_e32 v92, v191
	v_cvt_f32_f16_sdwa v93, v191 dst_sel:DWORD dst_unused:UNUSED_PAD src0_sel:WORD_1
	v_pk_fma_f32 v[92:93], v[94:95], v[110:111], v[92:93]
	s_nop 0
	v_cvt_pk_f16_f32 v107, v92, v93
	v_lshl_add_u64 v[92:93], s[56:57], 0, v[232:233]
	v_lshl_add_u64 v[100:101], v[92:93], 0, v[220:221]
	v_cvt_f32_f16_e32 v92, v184
	v_cvt_f32_f16_sdwa v93, v184 dst_sel:DWORD dst_unused:UNUSED_PAD src0_sel:WORD_1
	global_store_dwordx4 v[100:101], v[104:107], off
	v_pk_fma_f32 v[84:85], v[84:85], v[96:97], v[92:93]
	s_nop 0
	v_cvt_pk_f16_f32 v92, v84, v85
	v_cvt_f32_f16_e32 v84, v186
	v_cvt_f32_f16_sdwa v85, v186 dst_sel:DWORD dst_unused:UNUSED_PAD src0_sel:WORD_1
	v_pk_fma_f32 v[80:81], v[80:81], v[88:89], v[84:85]
	s_nop 0
	v_cvt_pk_f16_f32 v94, v80, v81
	v_cvt_f32_f16_e32 v80, v185
	v_cvt_f32_f16_sdwa v81, v185 dst_sel:DWORD dst_unused:UNUSED_PAD src0_sel:WORD_1
	v_pk_fma_f32 v[80:81], v[86:87], v[98:99], v[80:81]
	s_nop 0
	v_cvt_pk_f16_f32 v93, v80, v81
	v_cvt_f32_f16_e32 v80, v187
	v_cvt_f32_f16_sdwa v81, v187 dst_sel:DWORD dst_unused:UNUSED_PAD src0_sel:WORD_1
	v_pk_fma_f32 v[80:81], v[82:83], v[90:91], v[80:81]
	s_nop 0
	v_cvt_pk_f16_f32 v95, v80, v81
	v_cvt_f32_f16_e32 v80, v180
	v_cvt_f32_f16_sdwa v81, v180 dst_sel:DWORD dst_unused:UNUSED_PAD src0_sel:WORD_1
	global_store_dwordx4 v[100:101], v[92:95], off offset:256
	v_pk_fma_f32 v[76:77], v[76:77], v[116:117], v[80:81]
	s_nop 0
	v_cvt_pk_f16_f32 v80, v76, v77
	v_cvt_f32_f16_e32 v76, v182
	v_cvt_f32_f16_sdwa v77, v182 dst_sel:DWORD dst_unused:UNUSED_PAD src0_sel:WORD_1
	v_pk_fma_f32 v[72:73], v[72:73], v[108:109], v[76:77]
	s_nop 0
	v_cvt_pk_f16_f32 v82, v72, v73
	v_cvt_f32_f16_e32 v72, v181
	v_cvt_f32_f16_sdwa v73, v181 dst_sel:DWORD dst_unused:UNUSED_PAD src0_sel:WORD_1
	v_pk_fma_f32 v[72:73], v[78:79], v[118:119], v[72:73]
	s_nop 0
	v_cvt_pk_f16_f32 v81, v72, v73
	v_cvt_f32_f16_e32 v72, v183
	v_cvt_f32_f16_sdwa v73, v183 dst_sel:DWORD dst_unused:UNUSED_PAD src0_sel:WORD_1
	v_pk_fma_f32 v[72:73], v[74:75], v[110:111], v[72:73]
	s_nop 0
	v_cvt_pk_f16_f32 v83, v72, v73
	v_lshl_add_u64 v[72:73], s[56:57], 0, v[230:231]
	v_lshl_add_u64 v[76:77], v[72:73], 0, v[220:221]
	v_cvt_f32_f16_e32 v72, v176
	v_cvt_f32_f16_sdwa v73, v176 dst_sel:DWORD dst_unused:UNUSED_PAD src0_sel:WORD_1
	global_store_dwordx4 v[76:77], v[80:83], off
	v_pk_fma_f32 v[68:69], v[68:69], v[96:97], v[72:73]
	s_nop 0
	v_cvt_pk_f16_f32 v72, v68, v69
	v_cvt_f32_f16_e32 v68, v178
	v_cvt_f32_f16_sdwa v69, v178 dst_sel:DWORD dst_unused:UNUSED_PAD src0_sel:WORD_1
	v_pk_fma_f32 v[64:65], v[64:65], v[88:89], v[68:69]
	s_nop 0
	v_cvt_pk_f16_f32 v74, v64, v65
	v_cvt_f32_f16_e32 v64, v177
	v_cvt_f32_f16_sdwa v65, v177 dst_sel:DWORD dst_unused:UNUSED_PAD src0_sel:WORD_1
	v_pk_fma_f32 v[64:65], v[70:71], v[98:99], v[64:65]
	s_nop 0
	v_cvt_pk_f16_f32 v73, v64, v65
	v_cvt_f32_f16_e32 v64, v179
	v_cvt_f32_f16_sdwa v65, v179 dst_sel:DWORD dst_unused:UNUSED_PAD src0_sel:WORD_1
	v_pk_fma_f32 v[64:65], v[66:67], v[90:91], v[64:65]
	s_nop 0
	v_cvt_pk_f16_f32 v75, v64, v65
	v_cvt_f32_f16_e32 v64, v172
	v_cvt_f32_f16_sdwa v65, v172 dst_sel:DWORD dst_unused:UNUSED_PAD src0_sel:WORD_1
	global_store_dwordx4 v[76:77], v[72:75], off offset:256
	v_pk_fma_f32 v[60:61], v[60:61], v[116:117], v[64:65]
	s_nop 0
	v_cvt_pk_f16_f32 v64, v60, v61
	v_cvt_f32_f16_e32 v60, v174
	v_cvt_f32_f16_sdwa v61, v174 dst_sel:DWORD dst_unused:UNUSED_PAD src0_sel:WORD_1
	v_pk_fma_f32 v[56:57], v[56:57], v[108:109], v[60:61]
	s_nop 0
	v_cvt_pk_f16_f32 v66, v56, v57
	v_cvt_f32_f16_e32 v56, v173
	v_cvt_f32_f16_sdwa v57, v173 dst_sel:DWORD dst_unused:UNUSED_PAD src0_sel:WORD_1
	v_pk_fma_f32 v[56:57], v[62:63], v[118:119], v[56:57]
	s_nop 0
	v_cvt_pk_f16_f32 v65, v56, v57
	v_cvt_f32_f16_e32 v56, v175
	v_cvt_f32_f16_sdwa v57, v175 dst_sel:DWORD dst_unused:UNUSED_PAD src0_sel:WORD_1
	v_pk_fma_f32 v[56:57], v[58:59], v[110:111], v[56:57]
	s_nop 0
	v_cvt_pk_f16_f32 v67, v56, v57
	v_lshl_add_u64 v[56:57], s[56:57], 0, v[228:229]
	v_lshl_add_u64 v[60:61], v[56:57], 0, v[220:221]
	v_cvt_f32_f16_e32 v56, v168
	v_cvt_f32_f16_sdwa v57, v168 dst_sel:DWORD dst_unused:UNUSED_PAD src0_sel:WORD_1
	global_store_dwordx4 v[60:61], v[64:67], off
	v_pk_fma_f32 v[52:53], v[52:53], v[96:97], v[56:57]
	s_nop 0
	v_cvt_pk_f16_f32 v56, v52, v53
	v_cvt_f32_f16_e32 v52, v170
	v_cvt_f32_f16_sdwa v53, v170 dst_sel:DWORD dst_unused:UNUSED_PAD src0_sel:WORD_1
	v_pk_fma_f32 v[48:49], v[48:49], v[88:89], v[52:53]
	s_nop 0
	v_cvt_pk_f16_f32 v58, v48, v49
	v_cvt_f32_f16_e32 v48, v169
	v_cvt_f32_f16_sdwa v49, v169 dst_sel:DWORD dst_unused:UNUSED_PAD src0_sel:WORD_1
	v_pk_fma_f32 v[48:49], v[54:55], v[98:99], v[48:49]
	s_nop 0
	v_cvt_pk_f16_f32 v57, v48, v49
	v_cvt_f32_f16_e32 v48, v171
	v_cvt_f32_f16_sdwa v49, v171 dst_sel:DWORD dst_unused:UNUSED_PAD src0_sel:WORD_1
	v_pk_fma_f32 v[48:49], v[50:51], v[90:91], v[48:49]
	s_nop 0
	v_cvt_pk_f16_f32 v59, v48, v49
	v_cvt_f32_f16_e32 v48, v164
	v_cvt_f32_f16_sdwa v49, v164 dst_sel:DWORD dst_unused:UNUSED_PAD src0_sel:WORD_1
	global_store_dwordx4 v[60:61], v[56:59], off offset:256
	v_pk_fma_f32 v[44:45], v[44:45], v[116:117], v[48:49]
	s_nop 0
	v_cvt_pk_f16_f32 v48, v44, v45
	v_cvt_f32_f16_e32 v44, v166
	v_cvt_f32_f16_sdwa v45, v166 dst_sel:DWORD dst_unused:UNUSED_PAD src0_sel:WORD_1
	v_pk_fma_f32 v[40:41], v[40:41], v[108:109], v[44:45]
	s_nop 0
	v_cvt_pk_f16_f32 v50, v40, v41
	v_cvt_f32_f16_e32 v40, v165
	v_cvt_f32_f16_sdwa v41, v165 dst_sel:DWORD dst_unused:UNUSED_PAD src0_sel:WORD_1
	v_pk_fma_f32 v[40:41], v[46:47], v[118:119], v[40:41]
	s_nop 0
	v_cvt_pk_f16_f32 v49, v40, v41
	v_cvt_f32_f16_e32 v40, v167
	v_cvt_f32_f16_sdwa v41, v167 dst_sel:DWORD dst_unused:UNUSED_PAD src0_sel:WORD_1
	v_pk_fma_f32 v[40:41], v[42:43], v[110:111], v[40:41]
	s_nop 0
	v_cvt_pk_f16_f32 v51, v40, v41
	v_lshl_add_u64 v[40:41], s[56:57], 0, v[226:227]
	v_lshl_add_u64 v[44:45], v[40:41], 0, v[220:221]
	v_cvt_f32_f16_e32 v40, v152
	v_cvt_f32_f16_sdwa v41, v152 dst_sel:DWORD dst_unused:UNUSED_PAD src0_sel:WORD_1
	global_store_dwordx4 v[44:45], v[48:51], off
	v_pk_fma_f32 v[36:37], v[36:37], v[96:97], v[40:41]
	s_nop 0
	v_cvt_pk_f16_f32 v40, v36, v37
	v_cvt_f32_f16_e32 v36, v154
	v_cvt_f32_f16_sdwa v37, v154 dst_sel:DWORD dst_unused:UNUSED_PAD src0_sel:WORD_1
	v_pk_fma_f32 v[32:33], v[32:33], v[88:89], v[36:37]
	s_nop 0
	v_cvt_pk_f16_f32 v42, v32, v33
	v_cvt_f32_f16_e32 v32, v153
	v_cvt_f32_f16_sdwa v33, v153 dst_sel:DWORD dst_unused:UNUSED_PAD src0_sel:WORD_1
	v_pk_fma_f32 v[32:33], v[38:39], v[98:99], v[32:33]
	s_nop 0
	v_cvt_pk_f16_f32 v41, v32, v33
	v_cvt_f32_f16_e32 v32, v155
	v_cvt_f32_f16_sdwa v33, v155 dst_sel:DWORD dst_unused:UNUSED_PAD src0_sel:WORD_1
	v_pk_fma_f32 v[32:33], v[34:35], v[90:91], v[32:33]
	s_nop 0
	v_cvt_pk_f16_f32 v43, v32, v33
	v_cvt_f32_f16_e32 v32, v148
	v_cvt_f32_f16_sdwa v33, v148 dst_sel:DWORD dst_unused:UNUSED_PAD src0_sel:WORD_1
	global_store_dwordx4 v[44:45], v[40:43], off offset:256
	v_pk_fma_f32 v[28:29], v[28:29], v[116:117], v[32:33]
	s_nop 0
	v_cvt_pk_f16_f32 v32, v28, v29
	v_cvt_f32_f16_e32 v28, v150
	v_cvt_f32_f16_sdwa v29, v150 dst_sel:DWORD dst_unused:UNUSED_PAD src0_sel:WORD_1
	v_pk_fma_f32 v[24:25], v[24:25], v[108:109], v[28:29]
	s_nop 0
	v_cvt_pk_f16_f32 v34, v24, v25
	v_cvt_f32_f16_e32 v24, v149
	v_cvt_f32_f16_sdwa v25, v149 dst_sel:DWORD dst_unused:UNUSED_PAD src0_sel:WORD_1
	v_pk_fma_f32 v[24:25], v[30:31], v[118:119], v[24:25]
	s_nop 0
	v_cvt_pk_f16_f32 v33, v24, v25
	v_cvt_f32_f16_e32 v24, v151
	v_cvt_f32_f16_sdwa v25, v151 dst_sel:DWORD dst_unused:UNUSED_PAD src0_sel:WORD_1
	v_pk_fma_f32 v[24:25], v[26:27], v[110:111], v[24:25]
	s_nop 0
	v_cvt_pk_f16_f32 v35, v24, v25
	v_lshl_add_u64 v[24:25], s[56:57], 0, v[224:225]
	v_lshl_add_u64 v[28:29], v[24:25], 0, v[220:221]
	v_cvt_f32_f16_e32 v24, v144
	v_cvt_f32_f16_sdwa v25, v144 dst_sel:DWORD dst_unused:UNUSED_PAD src0_sel:WORD_1
	global_store_dwordx4 v[28:29], v[32:35], off
	v_pk_fma_f32 v[20:21], v[20:21], v[96:97], v[24:25]
	s_nop 0
	v_cvt_pk_f16_f32 v24, v20, v21
	v_cvt_f32_f16_e32 v20, v146
	v_cvt_f32_f16_sdwa v21, v146 dst_sel:DWORD dst_unused:UNUSED_PAD src0_sel:WORD_1
	v_pk_fma_f32 v[16:17], v[16:17], v[88:89], v[20:21]
	s_nop 0
	v_cvt_pk_f16_f32 v26, v16, v17
	v_cvt_f32_f16_e32 v16, v145
	v_cvt_f32_f16_sdwa v17, v145 dst_sel:DWORD dst_unused:UNUSED_PAD src0_sel:WORD_1
	v_pk_fma_f32 v[16:17], v[22:23], v[98:99], v[16:17]
	s_nop 0
	v_cvt_pk_f16_f32 v25, v16, v17
	v_cvt_f32_f16_e32 v16, v147
	v_cvt_f32_f16_sdwa v17, v147 dst_sel:DWORD dst_unused:UNUSED_PAD src0_sel:WORD_1
	v_pk_fma_f32 v[16:17], v[18:19], v[90:91], v[16:17]
	s_nop 0
	v_cvt_pk_f16_f32 v27, v16, v17
	v_cvt_f32_f16_e32 v16, v136
	v_cvt_f32_f16_sdwa v17, v136 dst_sel:DWORD dst_unused:UNUSED_PAD src0_sel:WORD_1
	global_store_dwordx4 v[28:29], v[24:27], off offset:256
	v_pk_fma_f32 v[12:13], v[12:13], v[116:117], v[16:17]
	s_nop 0
	v_cvt_pk_f16_f32 v16, v12, v13
	v_cvt_f32_f16_e32 v12, v138
	v_cvt_f32_f16_sdwa v13, v138 dst_sel:DWORD dst_unused:UNUSED_PAD src0_sel:WORD_1
	v_pk_fma_f32 v[8:9], v[8:9], v[108:109], v[12:13]
	s_nop 0
	v_cvt_pk_f16_f32 v18, v8, v9
	v_cvt_f32_f16_e32 v8, v137
	v_cvt_f32_f16_sdwa v9, v137 dst_sel:DWORD dst_unused:UNUSED_PAD src0_sel:WORD_1
	v_pk_fma_f32 v[8:9], v[14:15], v[118:119], v[8:9]
	s_nop 0
	v_cvt_pk_f16_f32 v17, v8, v9
	v_cvt_f32_f16_e32 v8, v139
	v_cvt_f32_f16_sdwa v9, v139 dst_sel:DWORD dst_unused:UNUSED_PAD src0_sel:WORD_1
	v_pk_fma_f32 v[8:9], v[10:11], v[110:111], v[8:9]
	s_nop 0
	v_cvt_pk_f16_f32 v19, v8, v9
	v_lshl_add_u64 v[8:9], s[56:57], 0, v[222:223]
	v_lshl_add_u64 v[12:13], v[8:9], 0, v[220:221]
	v_cvt_f32_f16_e32 v8, v128
	v_cvt_f32_f16_sdwa v9, v128 dst_sel:DWORD dst_unused:UNUSED_PAD src0_sel:WORD_1
	global_store_dwordx4 v[12:13], v[16:19], off
	v_pk_fma_f32 v[4:5], v[4:5], v[96:97], v[8:9]
	s_nop 0
	v_cvt_pk_f16_f32 v8, v4, v5
	v_cvt_f32_f16_e32 v4, v130
	v_cvt_f32_f16_sdwa v5, v130 dst_sel:DWORD dst_unused:UNUSED_PAD src0_sel:WORD_1
	v_pk_fma_f32 v[0:1], v[0:1], v[88:89], v[4:5]
	s_nop 0
	v_cvt_pk_f16_f32 v10, v0, v1
	v_cvt_f32_f16_e32 v0, v129
	v_cvt_f32_f16_sdwa v1, v129 dst_sel:DWORD dst_unused:UNUSED_PAD src0_sel:WORD_1
	v_pk_fma_f32 v[0:1], v[6:7], v[98:99], v[0:1]
	s_nop 0
	v_cvt_pk_f16_f32 v9, v0, v1
	v_cvt_f32_f16_e32 v0, v131
	v_cvt_f32_f16_sdwa v1, v131 dst_sel:DWORD dst_unused:UNUSED_PAD src0_sel:WORD_1
	v_pk_fma_f32 v[0:1], v[2:3], v[90:91], v[0:1]
	s_nop 0
	v_cvt_pk_f16_f32 v11, v0, v1
	global_store_dwordx4 v[12:13], v[8:11], off offset:256
	s_cbranch_vccz .LBB0_1178
	s_waitcnt vmcnt(0)
	s_cmpk_gt_u32 s34, 0xff
	s_cbranch_scc1 .LBB0_1189
	s_barrier
